# P2 pooling items: hand-written path (16-token runs per wave, all rows loaded up front, sliding f32 window, cvt_pk RNE) for items after the first
# speedup vs baseline: 1.0137x; 1.0076x over previous
; template <int W> __device__ __forceinline__ void pool_item(const bfu* u, bfu* pooled, int tb) {
;     v4u r[W + 7];
; #pragma unroll
;     for (int j = 0; j < W + 7; ++j) { const int t = tb - (W - 1) + j; r[j] = (t >= 0) ? *(const v4u*)(u + (size_t)t * 1024) : (v4u){0u, 0u, 0u, 0u}; }
;     float a[8];
; #pragma unroll
;     for (int e = 0; e < 8; ++e) a[e] = 0.f;
; __global__ void __launch_bounds__(NWAVES * 64, 2) fwd_megakernel(Args args) {
;     ...
;             const unsigned n = (pidx < 512u) ? (pidx >> 1) : pidx - 256u;
;             if (n >= 768u) {
;                 const int pc = (int)(n - 768u);
; #pragma unroll 1
;                 for (int k2 = 0; k2 < 2; ++k2) { const int i = pc * 1024 + k2 * 512 + (int)threadIdx.x; const int ch = i & 127, tb = (i >> 7) * 8, gidx = ch >> 5;
;                     const bfu* up = Ub + ch * 8; bfu* pp = AB2 + 1024 + ch * 8;
;                     if (gidx == 0) pool_item<2>(up, pp, tb); else if (gidx == 1) pool_item<4>(up, pp, tb); else if (gidx == 2) pool_item<8>(up, pp, tb); else pool_item<16>(up, pp, tb); }
.LBB0_338:
	s_and_b64 vcc, exec, s[0:1]
	s_cbranch_vccz .LBB0_472
	s_cmpk_eq_u32 s86, 0x300
	s_cbranch_scc1 .Lpool_orig
	v_readfirstlane_b32 s62, v227
	s_mov_b32 s68, 0
	s_mov_b32 s69, -1
	s_mov_b32 s67, 0
	s_mov_b32 s71, 0
	s_lshr_b32 s62, s62, 6
	s_and_b32 s63, s62, 1
	s_lshr_b32 s64, s62, 1
	s_add_i32 s65, s86, 0xfffffd00
	s_lshl_b32 s65, s65, 2
	s_add_i32 s65, s65, s64
	s_lshl_b32 s65, s65, 4
	s_lshl_b32 s70, s65, 12
	s_add_i32 s66, s65, -15
	s_lshl_b32 s66, s66, 11
	s_cmp_eq_u32 s63, 0
	s_cbranch_scc1 .Lpool_even
	v_lshl_add_u64 v[0:1], v[222:223], 0, s[66:67]
	global_load_dwordx4 v[0:3], v[0:1], off
	s_add_u32 s66, s66, 0x800
	v_lshl_add_u64 v[4:5], v[222:223], 0, s[66:67]
	global_load_dwordx4 v[4:7], v[4:5], off
	s_add_u32 s66, s66, 0x800
	v_lshl_add_u64 v[8:9], v[222:223], 0, s[66:67]
	global_load_dwordx4 v[8:11], v[8:9], off
	s_add_u32 s66, s66, 0x800
	v_lshl_add_u64 v[12:13], v[222:223], 0, s[66:67]
	global_load_dwordx4 v[12:15], v[12:13], off
	s_add_u32 s66, s66, 0x800
	v_lshl_add_u64 v[16:17], v[222:223], 0, s[66:67]
	global_load_dwordx4 v[16:19], v[16:17], off
	s_add_u32 s66, s66, 0x800
	v_lshl_add_u64 v[20:21], v[222:223], 0, s[66:67]
	global_load_dwordx4 v[20:23], v[20:21], off
	s_add_u32 s66, s66, 0x800
	v_lshl_add_u64 v[24:25], v[222:223], 0, s[66:67]
	global_load_dwordx4 v[24:27], v[24:25], off
	s_add_u32 s66, s66, 0x800
	v_lshl_add_u64 v[28:29], v[222:223], 0, s[66:67]
	global_load_dwordx4 v[28:31], v[28:29], off
	s_add_u32 s66, s66, 0x800
	v_lshl_add_u64 v[32:33], v[222:223], 0, s[66:67]
	global_load_dwordx4 v[32:35], v[32:33], off
	s_add_u32 s66, s66, 0x800
	v_lshl_add_u64 v[36:37], v[222:223], 0, s[66:67]
	global_load_dwordx4 v[36:39], v[36:37], off
	s_add_u32 s66, s66, 0x800
	v_lshl_add_u64 v[40:41], v[222:223], 0, s[66:67]
	global_load_dwordx4 v[40:43], v[40:41], off
	s_add_u32 s66, s66, 0x800
	v_lshl_add_u64 v[44:45], v[222:223], 0, s[66:67]
	global_load_dwordx4 v[44:47], v[44:45], off
	s_add_u32 s66, s66, 0x800
	v_lshl_add_u64 v[48:49], v[222:223], 0, s[66:67]
	global_load_dwordx4 v[48:51], v[48:49], off
	s_add_u32 s66, s66, 0x800
	v_lshl_add_u64 v[52:53], v[222:223], 0, s[66:67]
	global_load_dwordx4 v[52:55], v[52:53], off
	s_add_u32 s66, s66, 0x800
	v_lshl_add_u64 v[56:57], v[222:223], 0, s[66:67]
	global_load_dwordx4 v[56:59], v[56:57], off
	s_add_u32 s66, s66, 0x800
	v_lshl_add_u64 v[60:61], v[222:223], 0, s[66:67]
	global_load_dwordx4 v[60:63], v[60:61], off
	s_add_u32 s66, s66, 0x800
	v_lshl_add_u64 v[64:65], v[222:223], 0, s[66:67]
	global_load_dwordx4 v[64:67], v[64:65], off
	s_add_u32 s66, s66, 0x800
	v_lshl_add_u64 v[68:69], v[222:223], 0, s[66:67]
	global_load_dwordx4 v[68:71], v[68:69], off
	s_add_u32 s66, s66, 0x800
	v_lshl_add_u64 v[72:73], v[222:223], 0, s[66:67]
	global_load_dwordx4 v[72:75], v[72:73], off
	s_add_u32 s66, s66, 0x800
	v_lshl_add_u64 v[76:77], v[222:223], 0, s[66:67]
	global_load_dwordx4 v[76:79], v[76:77], off
	s_add_u32 s66, s66, 0x800
	v_lshl_add_u64 v[80:81], v[222:223], 0, s[66:67]
	global_load_dwordx4 v[80:83], v[80:81], off
	s_add_u32 s66, s66, 0x800
	v_lshl_add_u64 v[84:85], v[222:223], 0, s[66:67]
	global_load_dwordx4 v[84:87], v[84:85], off
	s_add_u32 s66, s66, 0x800
	v_lshl_add_u64 v[88:89], v[222:223], 0, s[66:67]
	global_load_dwordx4 v[88:91], v[88:89], off
	s_add_u32 s66, s66, 0x800
	v_lshl_add_u64 v[92:93], v[222:223], 0, s[66:67]
	global_load_dwordx4 v[92:95], v[92:93], off
	s_add_u32 s66, s66, 0x800
	v_lshl_add_u64 v[96:97], v[222:223], 0, s[66:67]
	global_load_dwordx4 v[96:99], v[96:97], off
	s_add_u32 s66, s66, 0x800
	v_lshl_add_u64 v[100:101], v[222:223], 0, s[66:67]
	global_load_dwordx4 v[100:103], v[100:101], off
	s_add_u32 s66, s66, 0x800
	v_lshl_add_u64 v[104:105], v[222:223], 0, s[66:67]
	global_load_dwordx4 v[104:107], v[104:105], off
	s_add_u32 s66, s66, 0x800
	v_lshl_add_u64 v[108:109], v[222:223], 0, s[66:67]
	global_load_dwordx4 v[108:111], v[108:109], off
	s_add_u32 s66, s66, 0x800
	v_lshl_add_u64 v[112:113], v[222:223], 0, s[66:67]
	global_load_dwordx4 v[112:115], v[112:113], off
	s_add_u32 s66, s66, 0x800
	v_lshl_add_u64 v[116:117], v[222:223], 0, s[66:67]
	global_load_dwordx4 v[116:119], v[116:117], off
	s_add_u32 s66, s66, 0x800
	v_lshl_add_u64 v[120:121], v[222:223], 0, s[66:67]
	global_load_dwordx4 v[120:123], v[120:121], off
	s_add_u32 s66, s66, 0x800
	s_mov_b64 exec, -1
	v_mov_b32_e32 v148, 0x3e000000
	v_mov_b32_e32 v149, 0x3e000000
	v_mov_b32_e32 v124, 0
	v_mov_b32_e32 v125, 0
	v_mov_b32_e32 v126, 0
	v_mov_b32_e32 v127, 0
	v_mov_b32_e32 v128, 0
	v_mov_b32_e32 v129, 0
	v_mov_b32_e32 v130, 0
	v_mov_b32_e32 v131, 0
	s_mov_b64 exec, s[68:69]
	v_mov_b32_e32 v148, 0x3d800000
	v_mov_b32_e32 v149, 0x3d800000
	s_waitcnt vmcnt(30)
	v_lshlrev_b32_e32 v132, 16, v0
	v_and_b32_e32 v133, 0xffff0000, v0
	v_lshlrev_b32_e32 v134, 16, v1
	v_and_b32_e32 v135, 0xffff0000, v1
	v_lshlrev_b32_e32 v136, 16, v2
	v_and_b32_e32 v137, 0xffff0000, v2
	v_lshlrev_b32_e32 v138, 16, v3
	v_and_b32_e32 v139, 0xffff0000, v3
	v_pk_add_f32 v[124:125], v[124:125], v[132:133]
	v_pk_add_f32 v[126:127], v[126:127], v[134:135]
	v_pk_add_f32 v[128:129], v[128:129], v[136:137]
	v_pk_add_f32 v[130:131], v[130:131], v[138:139]
	s_waitcnt vmcnt(29)
	v_lshlrev_b32_e32 v132, 16, v4
	v_and_b32_e32 v133, 0xffff0000, v4
	v_lshlrev_b32_e32 v134, 16, v5
	v_and_b32_e32 v135, 0xffff0000, v5
	v_lshlrev_b32_e32 v136, 16, v6
	v_and_b32_e32 v137, 0xffff0000, v6
	v_lshlrev_b32_e32 v138, 16, v7
	v_and_b32_e32 v139, 0xffff0000, v7
	v_pk_add_f32 v[124:125], v[124:125], v[132:133]
	v_pk_add_f32 v[126:127], v[126:127], v[134:135]
	v_pk_add_f32 v[128:129], v[128:129], v[136:137]
	v_pk_add_f32 v[130:131], v[130:131], v[138:139]
	s_waitcnt vmcnt(28)
; __device__ __forceinline__ float bf_lo(unsigned w) { return __uint_as_float(w << 16); }
; __device__ __forceinline__ float bf_hi(unsigned w) { return __uint_as_float(w & 0xffff0000u); }
; template <int W> __device__ __forceinline__ void pool_item(const bfu* u, bfu* pooled, int tb) {
;     ...
; #pragma unroll
;     for (int j = 0; j < W - 1; ++j) { a[0] += pg8::bf_lo(r[j].x); a[1] += pg8::bf_hi(r[j].x); a[2] += pg8::bf_lo(r[j].y); a[3] += pg8::bf_hi(r[j].y); a[4] += pg8::bf_lo(r[j].z); a[5] += pg8::bf_hi(r[j].z); a[6] += pg8::bf_lo(r[j].w); a[7] += pg8::bf_hi(r[j].w); }
	v_lshlrev_b32_e32 v132, 16, v8
	v_and_b32_e32 v133, 0xffff0000, v8
	v_lshlrev_b32_e32 v134, 16, v9
	v_and_b32_e32 v135, 0xffff0000, v9
	v_lshlrev_b32_e32 v136, 16, v10
	v_and_b32_e32 v137, 0xffff0000, v10
	v_lshlrev_b32_e32 v138, 16, v11
	v_and_b32_e32 v139, 0xffff0000, v11
	v_pk_add_f32 v[124:125], v[124:125], v[132:133]
	v_pk_add_f32 v[126:127], v[126:127], v[134:135]
	v_pk_add_f32 v[128:129], v[128:129], v[136:137]
	v_pk_add_f32 v[130:131], v[130:131], v[138:139]
	s_waitcnt vmcnt(27)
	v_lshlrev_b32_e32 v132, 16, v12
	v_and_b32_e32 v133, 0xffff0000, v12
	v_lshlrev_b32_e32 v134, 16, v13
	v_and_b32_e32 v135, 0xffff0000, v13
	v_lshlrev_b32_e32 v136, 16, v14
	v_and_b32_e32 v137, 0xffff0000, v14
	v_lshlrev_b32_e32 v138, 16, v15
	v_and_b32_e32 v139, 0xffff0000, v15
	v_pk_add_f32 v[124:125], v[124:125], v[132:133]
	v_pk_add_f32 v[126:127], v[126:127], v[134:135]
	v_pk_add_f32 v[128:129], v[128:129], v[136:137]
	v_pk_add_f32 v[130:131], v[130:131], v[138:139]
	s_waitcnt vmcnt(26)
	v_lshlrev_b32_e32 v132, 16, v16
	v_and_b32_e32 v133, 0xffff0000, v16
	v_lshlrev_b32_e32 v134, 16, v17
	v_and_b32_e32 v135, 0xffff0000, v17
	v_lshlrev_b32_e32 v136, 16, v18
	v_and_b32_e32 v137, 0xffff0000, v18
	v_lshlrev_b32_e32 v138, 16, v19
	v_and_b32_e32 v139, 0xffff0000, v19
	v_pk_add_f32 v[124:125], v[124:125], v[132:133]
	v_pk_add_f32 v[126:127], v[126:127], v[134:135]
	v_pk_add_f32 v[128:129], v[128:129], v[136:137]
	v_pk_add_f32 v[130:131], v[130:131], v[138:139]
	s_waitcnt vmcnt(25)
	v_lshlrev_b32_e32 v132, 16, v20
	v_and_b32_e32 v133, 0xffff0000, v20
	v_lshlrev_b32_e32 v134, 16, v21
	v_and_b32_e32 v135, 0xffff0000, v21
	v_lshlrev_b32_e32 v136, 16, v22
	v_and_b32_e32 v137, 0xffff0000, v22
	v_lshlrev_b32_e32 v138, 16, v23
	v_and_b32_e32 v139, 0xffff0000, v23
	v_pk_add_f32 v[124:125], v[124:125], v[132:133]
	v_pk_add_f32 v[126:127], v[126:127], v[134:135]
	v_pk_add_f32 v[128:129], v[128:129], v[136:137]
	v_pk_add_f32 v[130:131], v[130:131], v[138:139]
	s_waitcnt vmcnt(24)
	v_lshlrev_b32_e32 v132, 16, v24
	v_and_b32_e32 v133, 0xffff0000, v24
	v_lshlrev_b32_e32 v134, 16, v25
	v_and_b32_e32 v135, 0xffff0000, v25
	v_lshlrev_b32_e32 v136, 16, v26
	v_and_b32_e32 v137, 0xffff0000, v26
	v_lshlrev_b32_e32 v138, 16, v27
	v_and_b32_e32 v139, 0xffff0000, v27
	v_pk_add_f32 v[124:125], v[124:125], v[132:133]
	v_pk_add_f32 v[126:127], v[126:127], v[134:135]
	v_pk_add_f32 v[128:129], v[128:129], v[136:137]
	v_pk_add_f32 v[130:131], v[130:131], v[138:139]
	s_waitcnt vmcnt(23)
	v_lshlrev_b32_e32 v132, 16, v28
	v_and_b32_e32 v133, 0xffff0000, v28
	v_lshlrev_b32_e32 v134, 16, v29
	v_and_b32_e32 v135, 0xffff0000, v29
	v_lshlrev_b32_e32 v136, 16, v30
	v_and_b32_e32 v137, 0xffff0000, v30
	v_lshlrev_b32_e32 v138, 16, v31
	v_and_b32_e32 v139, 0xffff0000, v31
	v_pk_add_f32 v[124:125], v[124:125], v[132:133]
	v_pk_add_f32 v[126:127], v[126:127], v[134:135]
	v_pk_add_f32 v[128:129], v[128:129], v[136:137]
	v_pk_add_f32 v[130:131], v[130:131], v[138:139]
	s_mov_b64 exec, -1
	s_waitcnt vmcnt(22)
	v_lshlrev_b32_e32 v132, 16, v32
	v_and_b32_e32 v133, 0xffff0000, v32
	v_lshlrev_b32_e32 v134, 16, v33
	v_and_b32_e32 v135, 0xffff0000, v33
	v_lshlrev_b32_e32 v136, 16, v34
	v_and_b32_e32 v137, 0xffff0000, v34
	v_lshlrev_b32_e32 v138, 16, v35
	v_and_b32_e32 v139, 0xffff0000, v35
	v_pk_add_f32 v[124:125], v[124:125], v[132:133]
	v_pk_add_f32 v[126:127], v[126:127], v[134:135]
	v_pk_add_f32 v[128:129], v[128:129], v[136:137]
	v_pk_add_f32 v[130:131], v[130:131], v[138:139]
	s_waitcnt vmcnt(21)
	v_lshlrev_b32_e32 v132, 16, v36
	v_and_b32_e32 v133, 0xffff0000, v36
	v_lshlrev_b32_e32 v134, 16, v37
	v_and_b32_e32 v135, 0xffff0000, v37
	v_lshlrev_b32_e32 v136, 16, v38
	v_and_b32_e32 v137, 0xffff0000, v38
	v_lshlrev_b32_e32 v138, 16, v39
	v_and_b32_e32 v139, 0xffff0000, v39
	v_pk_add_f32 v[124:125], v[124:125], v[132:133]
	v_pk_add_f32 v[126:127], v[126:127], v[134:135]
	v_pk_add_f32 v[128:129], v[128:129], v[136:137]
	v_pk_add_f32 v[130:131], v[130:131], v[138:139]
	s_waitcnt vmcnt(20)
	v_lshlrev_b32_e32 v132, 16, v40
	v_and_b32_e32 v133, 0xffff0000, v40
	v_lshlrev_b32_e32 v134, 16, v41
	v_and_b32_e32 v135, 0xffff0000, v41
	v_lshlrev_b32_e32 v136, 16, v42
	v_and_b32_e32 v137, 0xffff0000, v42
	v_lshlrev_b32_e32 v138, 16, v43
	v_and_b32_e32 v139, 0xffff0000, v43
	v_pk_add_f32 v[124:125], v[124:125], v[132:133]
	v_pk_add_f32 v[126:127], v[126:127], v[134:135]
	v_pk_add_f32 v[128:129], v[128:129], v[136:137]
	v_pk_add_f32 v[130:131], v[130:131], v[138:139]
	s_waitcnt vmcnt(19)
	v_lshlrev_b32_e32 v132, 16, v44
	v_and_b32_e32 v133, 0xffff0000, v44
	v_lshlrev_b32_e32 v134, 16, v45
	v_and_b32_e32 v135, 0xffff0000, v45
	v_lshlrev_b32_e32 v136, 16, v46
	v_and_b32_e32 v137, 0xffff0000, v46
	v_lshlrev_b32_e32 v138, 16, v47
	v_and_b32_e32 v139, 0xffff0000, v47
	v_pk_add_f32 v[124:125], v[124:125], v[132:133]
	v_pk_add_f32 v[126:127], v[126:127], v[134:135]
	v_pk_add_f32 v[128:129], v[128:129], v[136:137]
	v_pk_add_f32 v[130:131], v[130:131], v[138:139]
	s_waitcnt vmcnt(18)
	v_lshlrev_b32_e32 v132, 16, v48
	v_and_b32_e32 v133, 0xffff0000, v48
	v_lshlrev_b32_e32 v134, 16, v49
	v_and_b32_e32 v135, 0xffff0000, v49
	v_lshlrev_b32_e32 v136, 16, v50
	v_and_b32_e32 v137, 0xffff0000, v50
	v_lshlrev_b32_e32 v138, 16, v51
	v_and_b32_e32 v139, 0xffff0000, v51
	v_pk_add_f32 v[124:125], v[124:125], v[132:133]
	v_pk_add_f32 v[126:127], v[126:127], v[134:135]
	v_pk_add_f32 v[128:129], v[128:129], v[136:137]
	v_pk_add_f32 v[130:131], v[130:131], v[138:139]
	s_waitcnt vmcnt(17)
; __device__ __forceinline__ float bf_lo(unsigned w) { return __uint_as_float(w << 16); }
; __device__ __forceinline__ float bf_hi(unsigned w) { return __uint_as_float(w & 0xffff0000u); }
; __device__ __forceinline__ unsigned pk2(float lo, float hi) { return f2bf(lo) | (f2bf(hi) << 16); }
; template <int W> __device__ __forceinline__ void pool_item(const bfu* u, bfu* pooled, int tb) {
;     ...
; #pragma unroll
;     for (int k = 0; k < 8; ++k) {
;         const v4u c = r[W - 1 + k]; const int t = tb + k;
;         const float cv[8] = {pg8::bf_lo(c.x), pg8::bf_hi(c.x), pg8::bf_lo(c.y), pg8::bf_hi(c.y), pg8::bf_lo(c.z), pg8::bf_hi(c.z), pg8::bf_lo(c.w), pg8::bf_hi(c.w)};
; #pragma unroll
;         for (int e = 0; e < 8; ++e) a[e] += cv[e];
;         const float inv = 1.f / (float)((t + 1) < W ? (t + 1) : W);
;         v4u o; o.x = pk2(a[0] * inv - cv[0], a[1] * inv - cv[1]); o.y = pk2(a[2] * inv - cv[2], a[3] * inv - cv[3]); o.z = pk2(a[4] * inv - cv[4], a[5] * inv - cv[5]); o.w = pk2(a[6] * inv - cv[6], a[7] * inv - cv[7]);
;         *(v4u*)(pooled + (size_t)t * 2048) = o;
;         const v4u d = r[k];
;         a[0] -= pg8::bf_lo(d.x); a[1] -= pg8::bf_hi(d.x); a[2] -= pg8::bf_lo(d.y); a[3] -= pg8::bf_hi(d.y); a[4] -= pg8::bf_lo(d.z); a[5] -= pg8::bf_hi(d.z); a[6] -= pg8::bf_lo(d.w); a[7] -= pg8::bf_hi(d.w);
;     }
	v_lshlrev_b32_e32 v132, 16, v52
	v_and_b32_e32 v133, 0xffff0000, v52
	v_lshlrev_b32_e32 v134, 16, v53
	v_and_b32_e32 v135, 0xffff0000, v53
	v_lshlrev_b32_e32 v136, 16, v54
	v_and_b32_e32 v137, 0xffff0000, v54
	v_lshlrev_b32_e32 v138, 16, v55
	v_and_b32_e32 v139, 0xffff0000, v55
	v_pk_add_f32 v[124:125], v[124:125], v[132:133]
	v_pk_add_f32 v[126:127], v[126:127], v[134:135]
	v_pk_add_f32 v[128:129], v[128:129], v[136:137]
	v_pk_add_f32 v[130:131], v[130:131], v[138:139]
	s_waitcnt vmcnt(16)
	v_lshlrev_b32_e32 v132, 16, v56
	v_and_b32_e32 v133, 0xffff0000, v56
	v_lshlrev_b32_e32 v134, 16, v57
	v_and_b32_e32 v135, 0xffff0000, v57
	v_lshlrev_b32_e32 v136, 16, v58
	v_and_b32_e32 v137, 0xffff0000, v58
	v_lshlrev_b32_e32 v138, 16, v59
	v_and_b32_e32 v139, 0xffff0000, v59
	v_pk_add_f32 v[124:125], v[124:125], v[132:133]
	v_pk_add_f32 v[126:127], v[126:127], v[134:135]
	v_pk_add_f32 v[128:129], v[128:129], v[136:137]
	v_pk_add_f32 v[130:131], v[130:131], v[138:139]
	s_waitcnt vmcnt(15)
	v_lshlrev_b32_e32 v132, 16, v60
	v_and_b32_e32 v133, 0xffff0000, v60
	v_lshlrev_b32_e32 v134, 16, v61
	v_and_b32_e32 v135, 0xffff0000, v61
	v_lshlrev_b32_e32 v136, 16, v62
	v_and_b32_e32 v137, 0xffff0000, v62
	v_lshlrev_b32_e32 v138, 16, v63
	v_and_b32_e32 v139, 0xffff0000, v63
	v_pk_add_f32 v[124:125], v[124:125], v[132:133]
	v_pk_add_f32 v[126:127], v[126:127], v[134:135]
	v_pk_add_f32 v[128:129], v[128:129], v[136:137]
	v_pk_add_f32 v[130:131], v[130:131], v[138:139]
	v_pk_fma_f32 v[132:133], v[148:149], v[124:125], v[132:133] neg_lo:[0,0,1] neg_hi:[0,0,1]
	v_pk_fma_f32 v[134:135], v[148:149], v[126:127], v[134:135] neg_lo:[0,0,1] neg_hi:[0,0,1]
	v_pk_fma_f32 v[136:137], v[148:149], v[128:129], v[136:137] neg_lo:[0,0,1] neg_hi:[0,0,1]
	v_pk_fma_f32 v[138:139], v[148:149], v[130:131], v[138:139] neg_lo:[0,0,1] neg_hi:[0,0,1]
	v_cvt_pk_bf16_f32 v140, v132, v133
	v_cvt_pk_bf16_f32 v141, v134, v135
	v_cvt_pk_bf16_f32 v142, v136, v137
	v_cvt_pk_bf16_f32 v143, v138, v139
	v_lshl_add_u64 v[150:151], v[224:225], 0, s[70:71]
	s_add_u32 s70, s70, 0x1000
	global_store_dwordx4 v[150:151], v[140:143], off
	v_cndmask_b32_e64 v144, v32, v0, s[68:69]
	v_cndmask_b32_e64 v145, v33, v1, s[68:69]
	v_cndmask_b32_e64 v146, v34, v2, s[68:69]
	v_cndmask_b32_e64 v147, v35, v3, s[68:69]
	v_lshlrev_b32_e32 v132, 16, v144
	v_and_b32_e32 v133, 0xffff0000, v144
	v_lshlrev_b32_e32 v134, 16, v145
	v_and_b32_e32 v135, 0xffff0000, v145
	v_lshlrev_b32_e32 v136, 16, v146
	v_and_b32_e32 v137, 0xffff0000, v146
	v_lshlrev_b32_e32 v138, 16, v147
	v_and_b32_e32 v139, 0xffff0000, v147
	v_pk_add_f32 v[124:125], v[124:125], v[132:133] neg_lo:[0,1] neg_hi:[0,1]
	v_pk_add_f32 v[126:127], v[126:127], v[134:135] neg_lo:[0,1] neg_hi:[0,1]
	v_pk_add_f32 v[128:129], v[128:129], v[136:137] neg_lo:[0,1] neg_hi:[0,1]
	v_pk_add_f32 v[130:131], v[130:131], v[138:139] neg_lo:[0,1] neg_hi:[0,1]
	s_waitcnt vmcnt(15)
	v_lshlrev_b32_e32 v132, 16, v64
	v_and_b32_e32 v133, 0xffff0000, v64
	v_lshlrev_b32_e32 v134, 16, v65
	v_and_b32_e32 v135, 0xffff0000, v65
	v_lshlrev_b32_e32 v136, 16, v66
	v_and_b32_e32 v137, 0xffff0000, v66
	v_lshlrev_b32_e32 v138, 16, v67
	v_and_b32_e32 v139, 0xffff0000, v67
	v_pk_add_f32 v[124:125], v[124:125], v[132:133]
	v_pk_add_f32 v[126:127], v[126:127], v[134:135]
	v_pk_add_f32 v[128:129], v[128:129], v[136:137]
	v_pk_add_f32 v[130:131], v[130:131], v[138:139]
	v_pk_fma_f32 v[132:133], v[148:149], v[124:125], v[132:133] neg_lo:[0,0,1] neg_hi:[0,0,1]
	v_pk_fma_f32 v[134:135], v[148:149], v[126:127], v[134:135] neg_lo:[0,0,1] neg_hi:[0,0,1]
	v_pk_fma_f32 v[136:137], v[148:149], v[128:129], v[136:137] neg_lo:[0,0,1] neg_hi:[0,0,1]
	v_pk_fma_f32 v[138:139], v[148:149], v[130:131], v[138:139] neg_lo:[0,0,1] neg_hi:[0,0,1]
	v_cvt_pk_bf16_f32 v140, v132, v133
	v_cvt_pk_bf16_f32 v141, v134, v135
	v_cvt_pk_bf16_f32 v142, v136, v137
	v_cvt_pk_bf16_f32 v143, v138, v139
	v_lshl_add_u64 v[150:151], v[224:225], 0, s[70:71]
	s_add_u32 s70, s70, 0x1000
	global_store_dwordx4 v[150:151], v[140:143], off
	v_cndmask_b32_e64 v144, v36, v4, s[68:69]
	v_cndmask_b32_e64 v145, v37, v5, s[68:69]
	v_cndmask_b32_e64 v146, v38, v6, s[68:69]
	v_cndmask_b32_e64 v147, v39, v7, s[68:69]
	v_lshlrev_b32_e32 v132, 16, v144
	v_and_b32_e32 v133, 0xffff0000, v144
	v_lshlrev_b32_e32 v134, 16, v145
	v_and_b32_e32 v135, 0xffff0000, v145
	v_lshlrev_b32_e32 v136, 16, v146
	v_and_b32_e32 v137, 0xffff0000, v146
	v_lshlrev_b32_e32 v138, 16, v147
	v_and_b32_e32 v139, 0xffff0000, v147
	v_pk_add_f32 v[124:125], v[124:125], v[132:133] neg_lo:[0,1] neg_hi:[0,1]
	v_pk_add_f32 v[126:127], v[126:127], v[134:135] neg_lo:[0,1] neg_hi:[0,1]
	v_pk_add_f32 v[128:129], v[128:129], v[136:137] neg_lo:[0,1] neg_hi:[0,1]
	v_pk_add_f32 v[130:131], v[130:131], v[138:139] neg_lo:[0,1] neg_hi:[0,1]
	s_waitcnt vmcnt(15)
; __device__ __forceinline__ float bf_lo(unsigned w) { return __uint_as_float(w << 16); }
; __device__ __forceinline__ float bf_hi(unsigned w) { return __uint_as_float(w & 0xffff0000u); }
; __device__ __forceinline__ unsigned pk2(float lo, float hi) { return f2bf(lo) | (f2bf(hi) << 16); }
; template <int W> __device__ __forceinline__ void pool_item(const bfu* u, bfu* pooled, int tb) {
;     ...
;     for (int k = 0; k < 8; ++k) {
;         const v4u c = r[W - 1 + k]; const int t = tb + k;
;         const float cv[8] = {pg8::bf_lo(c.x), pg8::bf_hi(c.x), pg8::bf_lo(c.y), pg8::bf_hi(c.y), pg8::bf_lo(c.z), pg8::bf_hi(c.z), pg8::bf_lo(c.w), pg8::bf_hi(c.w)};
; #pragma unroll
;         for (int e = 0; e < 8; ++e) a[e] += cv[e];
;         const float inv = 1.f / (float)((t + 1) < W ? (t + 1) : W);
;         v4u o; o.x = pk2(a[0] * inv - cv[0], a[1] * inv - cv[1]); o.y = pk2(a[2] * inv - cv[2], a[3] * inv - cv[3]); o.z = pk2(a[4] * inv - cv[4], a[5] * inv - cv[5]); o.w = pk2(a[6] * inv - cv[6], a[7] * inv - cv[7]);
;         *(v4u*)(pooled + (size_t)t * 2048) = o;
;         const v4u d = r[k];
;         a[0] -= pg8::bf_lo(d.x); a[1] -= pg8::bf_hi(d.x); a[2] -= pg8::bf_lo(d.y); a[3] -= pg8::bf_hi(d.y); a[4] -= pg8::bf_lo(d.z); a[5] -= pg8::bf_hi(d.z); a[6] -= pg8::bf_lo(d.w); a[7] -= pg8::bf_hi(d.w);
;     }
	v_lshlrev_b32_e32 v132, 16, v68
	v_and_b32_e32 v133, 0xffff0000, v68
	v_lshlrev_b32_e32 v134, 16, v69
	v_and_b32_e32 v135, 0xffff0000, v69
	v_lshlrev_b32_e32 v136, 16, v70
	v_and_b32_e32 v137, 0xffff0000, v70
	v_lshlrev_b32_e32 v138, 16, v71
	v_and_b32_e32 v139, 0xffff0000, v71
	v_pk_add_f32 v[124:125], v[124:125], v[132:133]
	v_pk_add_f32 v[126:127], v[126:127], v[134:135]
	v_pk_add_f32 v[128:129], v[128:129], v[136:137]
	v_pk_add_f32 v[130:131], v[130:131], v[138:139]
	v_pk_fma_f32 v[132:133], v[148:149], v[124:125], v[132:133] neg_lo:[0,0,1] neg_hi:[0,0,1]
	v_pk_fma_f32 v[134:135], v[148:149], v[126:127], v[134:135] neg_lo:[0,0,1] neg_hi:[0,0,1]
	v_pk_fma_f32 v[136:137], v[148:149], v[128:129], v[136:137] neg_lo:[0,0,1] neg_hi:[0,0,1]
	v_pk_fma_f32 v[138:139], v[148:149], v[130:131], v[138:139] neg_lo:[0,0,1] neg_hi:[0,0,1]
	v_cvt_pk_bf16_f32 v140, v132, v133
	v_cvt_pk_bf16_f32 v141, v134, v135
	v_cvt_pk_bf16_f32 v142, v136, v137
	v_cvt_pk_bf16_f32 v143, v138, v139
	v_lshl_add_u64 v[150:151], v[224:225], 0, s[70:71]
	s_add_u32 s70, s70, 0x1000
	global_store_dwordx4 v[150:151], v[140:143], off
	v_cndmask_b32_e64 v144, v40, v8, s[68:69]
	v_cndmask_b32_e64 v145, v41, v9, s[68:69]
	v_cndmask_b32_e64 v146, v42, v10, s[68:69]
	v_cndmask_b32_e64 v147, v43, v11, s[68:69]
	v_lshlrev_b32_e32 v132, 16, v144
	v_and_b32_e32 v133, 0xffff0000, v144
	v_lshlrev_b32_e32 v134, 16, v145
	v_and_b32_e32 v135, 0xffff0000, v145
	v_lshlrev_b32_e32 v136, 16, v146
	v_and_b32_e32 v137, 0xffff0000, v146
	v_lshlrev_b32_e32 v138, 16, v147
	v_and_b32_e32 v139, 0xffff0000, v147
	v_pk_add_f32 v[124:125], v[124:125], v[132:133] neg_lo:[0,1] neg_hi:[0,1]
	v_pk_add_f32 v[126:127], v[126:127], v[134:135] neg_lo:[0,1] neg_hi:[0,1]
	v_pk_add_f32 v[128:129], v[128:129], v[136:137] neg_lo:[0,1] neg_hi:[0,1]
	v_pk_add_f32 v[130:131], v[130:131], v[138:139] neg_lo:[0,1] neg_hi:[0,1]
	s_waitcnt vmcnt(15)
	v_lshlrev_b32_e32 v132, 16, v72
	v_and_b32_e32 v133, 0xffff0000, v72
	v_lshlrev_b32_e32 v134, 16, v73
	v_and_b32_e32 v135, 0xffff0000, v73
	v_lshlrev_b32_e32 v136, 16, v74
	v_and_b32_e32 v137, 0xffff0000, v74
	v_lshlrev_b32_e32 v138, 16, v75
	v_and_b32_e32 v139, 0xffff0000, v75
	v_pk_add_f32 v[124:125], v[124:125], v[132:133]
	v_pk_add_f32 v[126:127], v[126:127], v[134:135]
	v_pk_add_f32 v[128:129], v[128:129], v[136:137]
	v_pk_add_f32 v[130:131], v[130:131], v[138:139]
	v_pk_fma_f32 v[132:133], v[148:149], v[124:125], v[132:133] neg_lo:[0,0,1] neg_hi:[0,0,1]
	v_pk_fma_f32 v[134:135], v[148:149], v[126:127], v[134:135] neg_lo:[0,0,1] neg_hi:[0,0,1]
	v_pk_fma_f32 v[136:137], v[148:149], v[128:129], v[136:137] neg_lo:[0,0,1] neg_hi:[0,0,1]
	v_pk_fma_f32 v[138:139], v[148:149], v[130:131], v[138:139] neg_lo:[0,0,1] neg_hi:[0,0,1]
	v_cvt_pk_bf16_f32 v140, v132, v133
	v_cvt_pk_bf16_f32 v141, v134, v135
	v_cvt_pk_bf16_f32 v142, v136, v137
	v_cvt_pk_bf16_f32 v143, v138, v139
	v_lshl_add_u64 v[150:151], v[224:225], 0, s[70:71]
	s_add_u32 s70, s70, 0x1000
	global_store_dwordx4 v[150:151], v[140:143], off
	v_cndmask_b32_e64 v144, v44, v12, s[68:69]
	v_cndmask_b32_e64 v145, v45, v13, s[68:69]
	v_cndmask_b32_e64 v146, v46, v14, s[68:69]
	v_cndmask_b32_e64 v147, v47, v15, s[68:69]
	v_lshlrev_b32_e32 v132, 16, v144
	v_and_b32_e32 v133, 0xffff0000, v144
	v_lshlrev_b32_e32 v134, 16, v145
	v_and_b32_e32 v135, 0xffff0000, v145
	v_lshlrev_b32_e32 v136, 16, v146
	v_and_b32_e32 v137, 0xffff0000, v146
	v_lshlrev_b32_e32 v138, 16, v147
	v_and_b32_e32 v139, 0xffff0000, v147
	v_pk_add_f32 v[124:125], v[124:125], v[132:133] neg_lo:[0,1] neg_hi:[0,1]
	v_pk_add_f32 v[126:127], v[126:127], v[134:135] neg_lo:[0,1] neg_hi:[0,1]
	v_pk_add_f32 v[128:129], v[128:129], v[136:137] neg_lo:[0,1] neg_hi:[0,1]
	v_pk_add_f32 v[130:131], v[130:131], v[138:139] neg_lo:[0,1] neg_hi:[0,1]
	s_waitcnt vmcnt(15)
	v_lshlrev_b32_e32 v132, 16, v76
	v_and_b32_e32 v133, 0xffff0000, v76
	v_lshlrev_b32_e32 v134, 16, v77
	v_and_b32_e32 v135, 0xffff0000, v77
	v_lshlrev_b32_e32 v136, 16, v78
	v_and_b32_e32 v137, 0xffff0000, v78
	v_lshlrev_b32_e32 v138, 16, v79
	v_and_b32_e32 v139, 0xffff0000, v79
	v_pk_add_f32 v[124:125], v[124:125], v[132:133]
	v_pk_add_f32 v[126:127], v[126:127], v[134:135]
	v_pk_add_f32 v[128:129], v[128:129], v[136:137]
	v_pk_add_f32 v[130:131], v[130:131], v[138:139]
	v_pk_fma_f32 v[132:133], v[148:149], v[124:125], v[132:133] neg_lo:[0,0,1] neg_hi:[0,0,1]
	v_pk_fma_f32 v[134:135], v[148:149], v[126:127], v[134:135] neg_lo:[0,0,1] neg_hi:[0,0,1]
	v_pk_fma_f32 v[136:137], v[148:149], v[128:129], v[136:137] neg_lo:[0,0,1] neg_hi:[0,0,1]
	v_pk_fma_f32 v[138:139], v[148:149], v[130:131], v[138:139] neg_lo:[0,0,1] neg_hi:[0,0,1]
	v_cvt_pk_bf16_f32 v140, v132, v133
	v_cvt_pk_bf16_f32 v141, v134, v135
	v_cvt_pk_bf16_f32 v142, v136, v137
	v_cvt_pk_bf16_f32 v143, v138, v139
	v_lshl_add_u64 v[150:151], v[224:225], 0, s[70:71]
	s_add_u32 s70, s70, 0x1000
	global_store_dwordx4 v[150:151], v[140:143], off
	v_cndmask_b32_e64 v144, v48, v16, s[68:69]
	v_cndmask_b32_e64 v145, v49, v17, s[68:69]
	v_cndmask_b32_e64 v146, v50, v18, s[68:69]
	v_cndmask_b32_e64 v147, v51, v19, s[68:69]
	v_lshlrev_b32_e32 v132, 16, v144
	v_and_b32_e32 v133, 0xffff0000, v144
	v_lshlrev_b32_e32 v134, 16, v145
	v_and_b32_e32 v135, 0xffff0000, v145
	v_lshlrev_b32_e32 v136, 16, v146
	v_and_b32_e32 v137, 0xffff0000, v146
	v_lshlrev_b32_e32 v138, 16, v147
	v_and_b32_e32 v139, 0xffff0000, v147
	v_pk_add_f32 v[124:125], v[124:125], v[132:133] neg_lo:[0,1] neg_hi:[0,1]
	v_pk_add_f32 v[126:127], v[126:127], v[134:135] neg_lo:[0,1] neg_hi:[0,1]
	v_pk_add_f32 v[128:129], v[128:129], v[136:137] neg_lo:[0,1] neg_hi:[0,1]
	v_pk_add_f32 v[130:131], v[130:131], v[138:139] neg_lo:[0,1] neg_hi:[0,1]
	s_waitcnt vmcnt(15)
; __device__ __forceinline__ float bf_lo(unsigned w) { return __uint_as_float(w << 16); }
; __device__ __forceinline__ float bf_hi(unsigned w) { return __uint_as_float(w & 0xffff0000u); }
; __device__ __forceinline__ unsigned pk2(float lo, float hi) { return f2bf(lo) | (f2bf(hi) << 16); }
; template <int W> __device__ __forceinline__ void pool_item(const bfu* u, bfu* pooled, int tb) {
;     ...
;     for (int k = 0; k < 8; ++k) {
;         const v4u c = r[W - 1 + k]; const int t = tb + k;
;         const float cv[8] = {pg8::bf_lo(c.x), pg8::bf_hi(c.x), pg8::bf_lo(c.y), pg8::bf_hi(c.y), pg8::bf_lo(c.z), pg8::bf_hi(c.z), pg8::bf_lo(c.w), pg8::bf_hi(c.w)};
; #pragma unroll
;         for (int e = 0; e < 8; ++e) a[e] += cv[e];
;         const float inv = 1.f / (float)((t + 1) < W ? (t + 1) : W);
;         v4u o; o.x = pk2(a[0] * inv - cv[0], a[1] * inv - cv[1]); o.y = pk2(a[2] * inv - cv[2], a[3] * inv - cv[3]); o.z = pk2(a[4] * inv - cv[4], a[5] * inv - cv[5]); o.w = pk2(a[6] * inv - cv[6], a[7] * inv - cv[7]);
;         *(v4u*)(pooled + (size_t)t * 2048) = o;
;         const v4u d = r[k];
;         a[0] -= pg8::bf_lo(d.x); a[1] -= pg8::bf_hi(d.x); a[2] -= pg8::bf_lo(d.y); a[3] -= pg8::bf_hi(d.y); a[4] -= pg8::bf_lo(d.z); a[5] -= pg8::bf_hi(d.z); a[6] -= pg8::bf_lo(d.w); a[7] -= pg8::bf_hi(d.w);
;     }
	v_lshlrev_b32_e32 v132, 16, v80
	v_and_b32_e32 v133, 0xffff0000, v80
	v_lshlrev_b32_e32 v134, 16, v81
	v_and_b32_e32 v135, 0xffff0000, v81
	v_lshlrev_b32_e32 v136, 16, v82
	v_and_b32_e32 v137, 0xffff0000, v82
	v_lshlrev_b32_e32 v138, 16, v83
	v_and_b32_e32 v139, 0xffff0000, v83
	v_pk_add_f32 v[124:125], v[124:125], v[132:133]
	v_pk_add_f32 v[126:127], v[126:127], v[134:135]
	v_pk_add_f32 v[128:129], v[128:129], v[136:137]
	v_pk_add_f32 v[130:131], v[130:131], v[138:139]
	v_pk_fma_f32 v[132:133], v[148:149], v[124:125], v[132:133] neg_lo:[0,0,1] neg_hi:[0,0,1]
	v_pk_fma_f32 v[134:135], v[148:149], v[126:127], v[134:135] neg_lo:[0,0,1] neg_hi:[0,0,1]
	v_pk_fma_f32 v[136:137], v[148:149], v[128:129], v[136:137] neg_lo:[0,0,1] neg_hi:[0,0,1]
	v_pk_fma_f32 v[138:139], v[148:149], v[130:131], v[138:139] neg_lo:[0,0,1] neg_hi:[0,0,1]
	v_cvt_pk_bf16_f32 v140, v132, v133
	v_cvt_pk_bf16_f32 v141, v134, v135
	v_cvt_pk_bf16_f32 v142, v136, v137
	v_cvt_pk_bf16_f32 v143, v138, v139
	v_lshl_add_u64 v[150:151], v[224:225], 0, s[70:71]
	s_add_u32 s70, s70, 0x1000
	global_store_dwordx4 v[150:151], v[140:143], off
	v_cndmask_b32_e64 v144, v52, v20, s[68:69]
	v_cndmask_b32_e64 v145, v53, v21, s[68:69]
	v_cndmask_b32_e64 v146, v54, v22, s[68:69]
	v_cndmask_b32_e64 v147, v55, v23, s[68:69]
	v_lshlrev_b32_e32 v132, 16, v144
	v_and_b32_e32 v133, 0xffff0000, v144
	v_lshlrev_b32_e32 v134, 16, v145
	v_and_b32_e32 v135, 0xffff0000, v145
	v_lshlrev_b32_e32 v136, 16, v146
	v_and_b32_e32 v137, 0xffff0000, v146
	v_lshlrev_b32_e32 v138, 16, v147
	v_and_b32_e32 v139, 0xffff0000, v147
	v_pk_add_f32 v[124:125], v[124:125], v[132:133] neg_lo:[0,1] neg_hi:[0,1]
	v_pk_add_f32 v[126:127], v[126:127], v[134:135] neg_lo:[0,1] neg_hi:[0,1]
	v_pk_add_f32 v[128:129], v[128:129], v[136:137] neg_lo:[0,1] neg_hi:[0,1]
	v_pk_add_f32 v[130:131], v[130:131], v[138:139] neg_lo:[0,1] neg_hi:[0,1]
	s_waitcnt vmcnt(15)
	v_lshlrev_b32_e32 v132, 16, v84
	v_and_b32_e32 v133, 0xffff0000, v84
	v_lshlrev_b32_e32 v134, 16, v85
	v_and_b32_e32 v135, 0xffff0000, v85
	v_lshlrev_b32_e32 v136, 16, v86
	v_and_b32_e32 v137, 0xffff0000, v86
	v_lshlrev_b32_e32 v138, 16, v87
	v_and_b32_e32 v139, 0xffff0000, v87
	v_pk_add_f32 v[124:125], v[124:125], v[132:133]
	v_pk_add_f32 v[126:127], v[126:127], v[134:135]
	v_pk_add_f32 v[128:129], v[128:129], v[136:137]
	v_pk_add_f32 v[130:131], v[130:131], v[138:139]
	v_pk_fma_f32 v[132:133], v[148:149], v[124:125], v[132:133] neg_lo:[0,0,1] neg_hi:[0,0,1]
	v_pk_fma_f32 v[134:135], v[148:149], v[126:127], v[134:135] neg_lo:[0,0,1] neg_hi:[0,0,1]
	v_pk_fma_f32 v[136:137], v[148:149], v[128:129], v[136:137] neg_lo:[0,0,1] neg_hi:[0,0,1]
	v_pk_fma_f32 v[138:139], v[148:149], v[130:131], v[138:139] neg_lo:[0,0,1] neg_hi:[0,0,1]
	v_cvt_pk_bf16_f32 v140, v132, v133
	v_cvt_pk_bf16_f32 v141, v134, v135
	v_cvt_pk_bf16_f32 v142, v136, v137
	v_cvt_pk_bf16_f32 v143, v138, v139
	v_lshl_add_u64 v[150:151], v[224:225], 0, s[70:71]
	s_add_u32 s70, s70, 0x1000
	global_store_dwordx4 v[150:151], v[140:143], off
	v_cndmask_b32_e64 v144, v56, v24, s[68:69]
	v_cndmask_b32_e64 v145, v57, v25, s[68:69]
	v_cndmask_b32_e64 v146, v58, v26, s[68:69]
	v_cndmask_b32_e64 v147, v59, v27, s[68:69]
	v_lshlrev_b32_e32 v132, 16, v144
	v_and_b32_e32 v133, 0xffff0000, v144
	v_lshlrev_b32_e32 v134, 16, v145
	v_and_b32_e32 v135, 0xffff0000, v145
	v_lshlrev_b32_e32 v136, 16, v146
	v_and_b32_e32 v137, 0xffff0000, v146
	v_lshlrev_b32_e32 v138, 16, v147
	v_and_b32_e32 v139, 0xffff0000, v147
	v_pk_add_f32 v[124:125], v[124:125], v[132:133] neg_lo:[0,1] neg_hi:[0,1]
	v_pk_add_f32 v[126:127], v[126:127], v[134:135] neg_lo:[0,1] neg_hi:[0,1]
	v_pk_add_f32 v[128:129], v[128:129], v[136:137] neg_lo:[0,1] neg_hi:[0,1]
	v_pk_add_f32 v[130:131], v[130:131], v[138:139] neg_lo:[0,1] neg_hi:[0,1]
	s_waitcnt vmcnt(15)
	v_lshlrev_b32_e32 v132, 16, v88
	v_and_b32_e32 v133, 0xffff0000, v88
	v_lshlrev_b32_e32 v134, 16, v89
	v_and_b32_e32 v135, 0xffff0000, v89
	v_lshlrev_b32_e32 v136, 16, v90
	v_and_b32_e32 v137, 0xffff0000, v90
	v_lshlrev_b32_e32 v138, 16, v91
	v_and_b32_e32 v139, 0xffff0000, v91
	v_pk_add_f32 v[124:125], v[124:125], v[132:133]
	v_pk_add_f32 v[126:127], v[126:127], v[134:135]
	v_pk_add_f32 v[128:129], v[128:129], v[136:137]
	v_pk_add_f32 v[130:131], v[130:131], v[138:139]
	v_pk_fma_f32 v[132:133], v[148:149], v[124:125], v[132:133] neg_lo:[0,0,1] neg_hi:[0,0,1]
	v_pk_fma_f32 v[134:135], v[148:149], v[126:127], v[134:135] neg_lo:[0,0,1] neg_hi:[0,0,1]
	v_pk_fma_f32 v[136:137], v[148:149], v[128:129], v[136:137] neg_lo:[0,0,1] neg_hi:[0,0,1]
	v_pk_fma_f32 v[138:139], v[148:149], v[130:131], v[138:139] neg_lo:[0,0,1] neg_hi:[0,0,1]
	v_cvt_pk_bf16_f32 v140, v132, v133
	v_cvt_pk_bf16_f32 v141, v134, v135
	v_cvt_pk_bf16_f32 v142, v136, v137
	v_cvt_pk_bf16_f32 v143, v138, v139
	v_lshl_add_u64 v[150:151], v[224:225], 0, s[70:71]
	s_add_u32 s70, s70, 0x1000
	global_store_dwordx4 v[150:151], v[140:143], off
	v_cndmask_b32_e64 v144, v60, v28, s[68:69]
	v_cndmask_b32_e64 v145, v61, v29, s[68:69]
	v_cndmask_b32_e64 v146, v62, v30, s[68:69]
	v_cndmask_b32_e64 v147, v63, v31, s[68:69]
	v_lshlrev_b32_e32 v132, 16, v144
	v_and_b32_e32 v133, 0xffff0000, v144
	v_lshlrev_b32_e32 v134, 16, v145
	v_and_b32_e32 v135, 0xffff0000, v145
	v_lshlrev_b32_e32 v136, 16, v146
	v_and_b32_e32 v137, 0xffff0000, v146
	v_lshlrev_b32_e32 v138, 16, v147
	v_and_b32_e32 v139, 0xffff0000, v147
	v_pk_add_f32 v[124:125], v[124:125], v[132:133] neg_lo:[0,1] neg_hi:[0,1]
	v_pk_add_f32 v[126:127], v[126:127], v[134:135] neg_lo:[0,1] neg_hi:[0,1]
	v_pk_add_f32 v[128:129], v[128:129], v[136:137] neg_lo:[0,1] neg_hi:[0,1]
	v_pk_add_f32 v[130:131], v[130:131], v[138:139] neg_lo:[0,1] neg_hi:[0,1]
	s_waitcnt vmcnt(15)
; __device__ __forceinline__ float bf_lo(unsigned w) { return __uint_as_float(w << 16); }
; __device__ __forceinline__ float bf_hi(unsigned w) { return __uint_as_float(w & 0xffff0000u); }
; __device__ __forceinline__ unsigned pk2(float lo, float hi) { return f2bf(lo) | (f2bf(hi) << 16); }
; template <int W> __device__ __forceinline__ void pool_item(const bfu* u, bfu* pooled, int tb) {
;     ...
;     for (int k = 0; k < 8; ++k) {
;         const v4u c = r[W - 1 + k]; const int t = tb + k;
;         const float cv[8] = {pg8::bf_lo(c.x), pg8::bf_hi(c.x), pg8::bf_lo(c.y), pg8::bf_hi(c.y), pg8::bf_lo(c.z), pg8::bf_hi(c.z), pg8::bf_lo(c.w), pg8::bf_hi(c.w)};
; #pragma unroll
;         for (int e = 0; e < 8; ++e) a[e] += cv[e];
;         const float inv = 1.f / (float)((t + 1) < W ? (t + 1) : W);
;         v4u o; o.x = pk2(a[0] * inv - cv[0], a[1] * inv - cv[1]); o.y = pk2(a[2] * inv - cv[2], a[3] * inv - cv[3]); o.z = pk2(a[4] * inv - cv[4], a[5] * inv - cv[5]); o.w = pk2(a[6] * inv - cv[6], a[7] * inv - cv[7]);
;         *(v4u*)(pooled + (size_t)t * 2048) = o;
;         const v4u d = r[k];
;         a[0] -= pg8::bf_lo(d.x); a[1] -= pg8::bf_hi(d.x); a[2] -= pg8::bf_lo(d.y); a[3] -= pg8::bf_hi(d.y); a[4] -= pg8::bf_lo(d.z); a[5] -= pg8::bf_hi(d.z); a[6] -= pg8::bf_lo(d.w); a[7] -= pg8::bf_hi(d.w);
;     }
	v_lshlrev_b32_e32 v132, 16, v92
	v_and_b32_e32 v133, 0xffff0000, v92
	v_lshlrev_b32_e32 v134, 16, v93
	v_and_b32_e32 v135, 0xffff0000, v93
	v_lshlrev_b32_e32 v136, 16, v94
	v_and_b32_e32 v137, 0xffff0000, v94
	v_lshlrev_b32_e32 v138, 16, v95
	v_and_b32_e32 v139, 0xffff0000, v95
	v_pk_add_f32 v[124:125], v[124:125], v[132:133]
	v_pk_add_f32 v[126:127], v[126:127], v[134:135]
	v_pk_add_f32 v[128:129], v[128:129], v[136:137]
	v_pk_add_f32 v[130:131], v[130:131], v[138:139]
	v_pk_fma_f32 v[132:133], v[148:149], v[124:125], v[132:133] neg_lo:[0,0,1] neg_hi:[0,0,1]
	v_pk_fma_f32 v[134:135], v[148:149], v[126:127], v[134:135] neg_lo:[0,0,1] neg_hi:[0,0,1]
	v_pk_fma_f32 v[136:137], v[148:149], v[128:129], v[136:137] neg_lo:[0,0,1] neg_hi:[0,0,1]
	v_pk_fma_f32 v[138:139], v[148:149], v[130:131], v[138:139] neg_lo:[0,0,1] neg_hi:[0,0,1]
	v_cvt_pk_bf16_f32 v140, v132, v133
	v_cvt_pk_bf16_f32 v141, v134, v135
	v_cvt_pk_bf16_f32 v142, v136, v137
	v_cvt_pk_bf16_f32 v143, v138, v139
	v_lshl_add_u64 v[150:151], v[224:225], 0, s[70:71]
	s_add_u32 s70, s70, 0x1000
	global_store_dwordx4 v[150:151], v[140:143], off
	v_cndmask_b32_e64 v144, v64, v32, s[68:69]
	v_cndmask_b32_e64 v145, v65, v33, s[68:69]
	v_cndmask_b32_e64 v146, v66, v34, s[68:69]
	v_cndmask_b32_e64 v147, v67, v35, s[68:69]
	v_lshlrev_b32_e32 v132, 16, v144
	v_and_b32_e32 v133, 0xffff0000, v144
	v_lshlrev_b32_e32 v134, 16, v145
	v_and_b32_e32 v135, 0xffff0000, v145
	v_lshlrev_b32_e32 v136, 16, v146
	v_and_b32_e32 v137, 0xffff0000, v146
	v_lshlrev_b32_e32 v138, 16, v147
	v_and_b32_e32 v139, 0xffff0000, v147
	v_pk_add_f32 v[124:125], v[124:125], v[132:133] neg_lo:[0,1] neg_hi:[0,1]
	v_pk_add_f32 v[126:127], v[126:127], v[134:135] neg_lo:[0,1] neg_hi:[0,1]
	v_pk_add_f32 v[128:129], v[128:129], v[136:137] neg_lo:[0,1] neg_hi:[0,1]
	v_pk_add_f32 v[130:131], v[130:131], v[138:139] neg_lo:[0,1] neg_hi:[0,1]
	s_waitcnt vmcnt(15)
	v_lshlrev_b32_e32 v132, 16, v96
	v_and_b32_e32 v133, 0xffff0000, v96
	v_lshlrev_b32_e32 v134, 16, v97
	v_and_b32_e32 v135, 0xffff0000, v97
	v_lshlrev_b32_e32 v136, 16, v98
	v_and_b32_e32 v137, 0xffff0000, v98
	v_lshlrev_b32_e32 v138, 16, v99
	v_and_b32_e32 v139, 0xffff0000, v99
	v_pk_add_f32 v[124:125], v[124:125], v[132:133]
	v_pk_add_f32 v[126:127], v[126:127], v[134:135]
	v_pk_add_f32 v[128:129], v[128:129], v[136:137]
	v_pk_add_f32 v[130:131], v[130:131], v[138:139]
	v_pk_fma_f32 v[132:133], v[148:149], v[124:125], v[132:133] neg_lo:[0,0,1] neg_hi:[0,0,1]
	v_pk_fma_f32 v[134:135], v[148:149], v[126:127], v[134:135] neg_lo:[0,0,1] neg_hi:[0,0,1]
	v_pk_fma_f32 v[136:137], v[148:149], v[128:129], v[136:137] neg_lo:[0,0,1] neg_hi:[0,0,1]
	v_pk_fma_f32 v[138:139], v[148:149], v[130:131], v[138:139] neg_lo:[0,0,1] neg_hi:[0,0,1]
	v_cvt_pk_bf16_f32 v140, v132, v133
	v_cvt_pk_bf16_f32 v141, v134, v135
	v_cvt_pk_bf16_f32 v142, v136, v137
	v_cvt_pk_bf16_f32 v143, v138, v139
	v_lshl_add_u64 v[150:151], v[224:225], 0, s[70:71]
	s_add_u32 s70, s70, 0x1000
	global_store_dwordx4 v[150:151], v[140:143], off
	v_cndmask_b32_e64 v144, v68, v36, s[68:69]
	v_cndmask_b32_e64 v145, v69, v37, s[68:69]
	v_cndmask_b32_e64 v146, v70, v38, s[68:69]
	v_cndmask_b32_e64 v147, v71, v39, s[68:69]
	v_lshlrev_b32_e32 v132, 16, v144
	v_and_b32_e32 v133, 0xffff0000, v144
	v_lshlrev_b32_e32 v134, 16, v145
	v_and_b32_e32 v135, 0xffff0000, v145
	v_lshlrev_b32_e32 v136, 16, v146
	v_and_b32_e32 v137, 0xffff0000, v146
	v_lshlrev_b32_e32 v138, 16, v147
	v_and_b32_e32 v139, 0xffff0000, v147
	v_pk_add_f32 v[124:125], v[124:125], v[132:133] neg_lo:[0,1] neg_hi:[0,1]
	v_pk_add_f32 v[126:127], v[126:127], v[134:135] neg_lo:[0,1] neg_hi:[0,1]
	v_pk_add_f32 v[128:129], v[128:129], v[136:137] neg_lo:[0,1] neg_hi:[0,1]
	v_pk_add_f32 v[130:131], v[130:131], v[138:139] neg_lo:[0,1] neg_hi:[0,1]
	s_waitcnt vmcnt(15)
	v_lshlrev_b32_e32 v132, 16, v100
	v_and_b32_e32 v133, 0xffff0000, v100
	v_lshlrev_b32_e32 v134, 16, v101
	v_and_b32_e32 v135, 0xffff0000, v101
	v_lshlrev_b32_e32 v136, 16, v102
	v_and_b32_e32 v137, 0xffff0000, v102
	v_lshlrev_b32_e32 v138, 16, v103
	v_and_b32_e32 v139, 0xffff0000, v103
	v_pk_add_f32 v[124:125], v[124:125], v[132:133]
	v_pk_add_f32 v[126:127], v[126:127], v[134:135]
	v_pk_add_f32 v[128:129], v[128:129], v[136:137]
	v_pk_add_f32 v[130:131], v[130:131], v[138:139]
	v_pk_fma_f32 v[132:133], v[148:149], v[124:125], v[132:133] neg_lo:[0,0,1] neg_hi:[0,0,1]
	v_pk_fma_f32 v[134:135], v[148:149], v[126:127], v[134:135] neg_lo:[0,0,1] neg_hi:[0,0,1]
	v_pk_fma_f32 v[136:137], v[148:149], v[128:129], v[136:137] neg_lo:[0,0,1] neg_hi:[0,0,1]
	v_pk_fma_f32 v[138:139], v[148:149], v[130:131], v[138:139] neg_lo:[0,0,1] neg_hi:[0,0,1]
	v_cvt_pk_bf16_f32 v140, v132, v133
	v_cvt_pk_bf16_f32 v141, v134, v135
	v_cvt_pk_bf16_f32 v142, v136, v137
	v_cvt_pk_bf16_f32 v143, v138, v139
	v_lshl_add_u64 v[150:151], v[224:225], 0, s[70:71]
	s_add_u32 s70, s70, 0x1000
	global_store_dwordx4 v[150:151], v[140:143], off
	v_cndmask_b32_e64 v144, v72, v40, s[68:69]
	v_cndmask_b32_e64 v145, v73, v41, s[68:69]
	v_cndmask_b32_e64 v146, v74, v42, s[68:69]
	v_cndmask_b32_e64 v147, v75, v43, s[68:69]
	v_lshlrev_b32_e32 v132, 16, v144
	v_and_b32_e32 v133, 0xffff0000, v144
	v_lshlrev_b32_e32 v134, 16, v145
	v_and_b32_e32 v135, 0xffff0000, v145
	v_lshlrev_b32_e32 v136, 16, v146
	v_and_b32_e32 v137, 0xffff0000, v146
	v_lshlrev_b32_e32 v138, 16, v147
	v_and_b32_e32 v139, 0xffff0000, v147
	v_pk_add_f32 v[124:125], v[124:125], v[132:133] neg_lo:[0,1] neg_hi:[0,1]
	v_pk_add_f32 v[126:127], v[126:127], v[134:135] neg_lo:[0,1] neg_hi:[0,1]
	v_pk_add_f32 v[128:129], v[128:129], v[136:137] neg_lo:[0,1] neg_hi:[0,1]
	v_pk_add_f32 v[130:131], v[130:131], v[138:139] neg_lo:[0,1] neg_hi:[0,1]
	s_waitcnt vmcnt(15)
; __device__ __forceinline__ float bf_lo(unsigned w) { return __uint_as_float(w << 16); }
; __device__ __forceinline__ float bf_hi(unsigned w) { return __uint_as_float(w & 0xffff0000u); }
; __device__ __forceinline__ unsigned pk2(float lo, float hi) { return f2bf(lo) | (f2bf(hi) << 16); }
; template <int W> __device__ __forceinline__ void pool_item(const bfu* u, bfu* pooled, int tb) {
;     ...
;     for (int k = 0; k < 8; ++k) {
;         const v4u c = r[W - 1 + k]; const int t = tb + k;
;         const float cv[8] = {pg8::bf_lo(c.x), pg8::bf_hi(c.x), pg8::bf_lo(c.y), pg8::bf_hi(c.y), pg8::bf_lo(c.z), pg8::bf_hi(c.z), pg8::bf_lo(c.w), pg8::bf_hi(c.w)};
; #pragma unroll
;         for (int e = 0; e < 8; ++e) a[e] += cv[e];
;         const float inv = 1.f / (float)((t + 1) < W ? (t + 1) : W);
;         v4u o; o.x = pk2(a[0] * inv - cv[0], a[1] * inv - cv[1]); o.y = pk2(a[2] * inv - cv[2], a[3] * inv - cv[3]); o.z = pk2(a[4] * inv - cv[4], a[5] * inv - cv[5]); o.w = pk2(a[6] * inv - cv[6], a[7] * inv - cv[7]);
;         *(v4u*)(pooled + (size_t)t * 2048) = o;
;         const v4u d = r[k];
;         a[0] -= pg8::bf_lo(d.x); a[1] -= pg8::bf_hi(d.x); a[2] -= pg8::bf_lo(d.y); a[3] -= pg8::bf_hi(d.y); a[4] -= pg8::bf_lo(d.z); a[5] -= pg8::bf_hi(d.z); a[6] -= pg8::bf_lo(d.w); a[7] -= pg8::bf_hi(d.w);
;     }
	v_lshlrev_b32_e32 v132, 16, v104
	v_and_b32_e32 v133, 0xffff0000, v104
	v_lshlrev_b32_e32 v134, 16, v105
	v_and_b32_e32 v135, 0xffff0000, v105
	v_lshlrev_b32_e32 v136, 16, v106
	v_and_b32_e32 v137, 0xffff0000, v106
	v_lshlrev_b32_e32 v138, 16, v107
	v_and_b32_e32 v139, 0xffff0000, v107
	v_pk_add_f32 v[124:125], v[124:125], v[132:133]
	v_pk_add_f32 v[126:127], v[126:127], v[134:135]
	v_pk_add_f32 v[128:129], v[128:129], v[136:137]
	v_pk_add_f32 v[130:131], v[130:131], v[138:139]
	v_pk_fma_f32 v[132:133], v[148:149], v[124:125], v[132:133] neg_lo:[0,0,1] neg_hi:[0,0,1]
	v_pk_fma_f32 v[134:135], v[148:149], v[126:127], v[134:135] neg_lo:[0,0,1] neg_hi:[0,0,1]
	v_pk_fma_f32 v[136:137], v[148:149], v[128:129], v[136:137] neg_lo:[0,0,1] neg_hi:[0,0,1]
	v_pk_fma_f32 v[138:139], v[148:149], v[130:131], v[138:139] neg_lo:[0,0,1] neg_hi:[0,0,1]
	v_cvt_pk_bf16_f32 v140, v132, v133
	v_cvt_pk_bf16_f32 v141, v134, v135
	v_cvt_pk_bf16_f32 v142, v136, v137
	v_cvt_pk_bf16_f32 v143, v138, v139
	v_lshl_add_u64 v[150:151], v[224:225], 0, s[70:71]
	s_add_u32 s70, s70, 0x1000
	global_store_dwordx4 v[150:151], v[140:143], off
	v_cndmask_b32_e64 v144, v76, v44, s[68:69]
	v_cndmask_b32_e64 v145, v77, v45, s[68:69]
	v_cndmask_b32_e64 v146, v78, v46, s[68:69]
	v_cndmask_b32_e64 v147, v79, v47, s[68:69]
	v_lshlrev_b32_e32 v132, 16, v144
	v_and_b32_e32 v133, 0xffff0000, v144
	v_lshlrev_b32_e32 v134, 16, v145
	v_and_b32_e32 v135, 0xffff0000, v145
	v_lshlrev_b32_e32 v136, 16, v146
	v_and_b32_e32 v137, 0xffff0000, v146
	v_lshlrev_b32_e32 v138, 16, v147
	v_and_b32_e32 v139, 0xffff0000, v147
	v_pk_add_f32 v[124:125], v[124:125], v[132:133] neg_lo:[0,1] neg_hi:[0,1]
	v_pk_add_f32 v[126:127], v[126:127], v[134:135] neg_lo:[0,1] neg_hi:[0,1]
	v_pk_add_f32 v[128:129], v[128:129], v[136:137] neg_lo:[0,1] neg_hi:[0,1]
	v_pk_add_f32 v[130:131], v[130:131], v[138:139] neg_lo:[0,1] neg_hi:[0,1]
	s_waitcnt vmcnt(15)
	v_lshlrev_b32_e32 v132, 16, v108
	v_and_b32_e32 v133, 0xffff0000, v108
	v_lshlrev_b32_e32 v134, 16, v109
	v_and_b32_e32 v135, 0xffff0000, v109
	v_lshlrev_b32_e32 v136, 16, v110
	v_and_b32_e32 v137, 0xffff0000, v110
	v_lshlrev_b32_e32 v138, 16, v111
	v_and_b32_e32 v139, 0xffff0000, v111
	v_pk_add_f32 v[124:125], v[124:125], v[132:133]
	v_pk_add_f32 v[126:127], v[126:127], v[134:135]
	v_pk_add_f32 v[128:129], v[128:129], v[136:137]
	v_pk_add_f32 v[130:131], v[130:131], v[138:139]
	v_pk_fma_f32 v[132:133], v[148:149], v[124:125], v[132:133] neg_lo:[0,0,1] neg_hi:[0,0,1]
	v_pk_fma_f32 v[134:135], v[148:149], v[126:127], v[134:135] neg_lo:[0,0,1] neg_hi:[0,0,1]
	v_pk_fma_f32 v[136:137], v[148:149], v[128:129], v[136:137] neg_lo:[0,0,1] neg_hi:[0,0,1]
	v_pk_fma_f32 v[138:139], v[148:149], v[130:131], v[138:139] neg_lo:[0,0,1] neg_hi:[0,0,1]
	v_cvt_pk_bf16_f32 v140, v132, v133
	v_cvt_pk_bf16_f32 v141, v134, v135
	v_cvt_pk_bf16_f32 v142, v136, v137
	v_cvt_pk_bf16_f32 v143, v138, v139
	v_lshl_add_u64 v[150:151], v[224:225], 0, s[70:71]
	s_add_u32 s70, s70, 0x1000
	global_store_dwordx4 v[150:151], v[140:143], off
	v_cndmask_b32_e64 v144, v80, v48, s[68:69]
	v_cndmask_b32_e64 v145, v81, v49, s[68:69]
	v_cndmask_b32_e64 v146, v82, v50, s[68:69]
	v_cndmask_b32_e64 v147, v83, v51, s[68:69]
	v_lshlrev_b32_e32 v132, 16, v144
	v_and_b32_e32 v133, 0xffff0000, v144
	v_lshlrev_b32_e32 v134, 16, v145
	v_and_b32_e32 v135, 0xffff0000, v145
	v_lshlrev_b32_e32 v136, 16, v146
	v_and_b32_e32 v137, 0xffff0000, v146
	v_lshlrev_b32_e32 v138, 16, v147
	v_and_b32_e32 v139, 0xffff0000, v147
	v_pk_add_f32 v[124:125], v[124:125], v[132:133] neg_lo:[0,1] neg_hi:[0,1]
	v_pk_add_f32 v[126:127], v[126:127], v[134:135] neg_lo:[0,1] neg_hi:[0,1]
	v_pk_add_f32 v[128:129], v[128:129], v[136:137] neg_lo:[0,1] neg_hi:[0,1]
	v_pk_add_f32 v[130:131], v[130:131], v[138:139] neg_lo:[0,1] neg_hi:[0,1]
	s_waitcnt vmcnt(15)
	v_lshlrev_b32_e32 v132, 16, v112
	v_and_b32_e32 v133, 0xffff0000, v112
	v_lshlrev_b32_e32 v134, 16, v113
	v_and_b32_e32 v135, 0xffff0000, v113
	v_lshlrev_b32_e32 v136, 16, v114
	v_and_b32_e32 v137, 0xffff0000, v114
	v_lshlrev_b32_e32 v138, 16, v115
	v_and_b32_e32 v139, 0xffff0000, v115
	v_pk_add_f32 v[124:125], v[124:125], v[132:133]
	v_pk_add_f32 v[126:127], v[126:127], v[134:135]
	v_pk_add_f32 v[128:129], v[128:129], v[136:137]
	v_pk_add_f32 v[130:131], v[130:131], v[138:139]
	v_pk_fma_f32 v[132:133], v[148:149], v[124:125], v[132:133] neg_lo:[0,0,1] neg_hi:[0,0,1]
	v_pk_fma_f32 v[134:135], v[148:149], v[126:127], v[134:135] neg_lo:[0,0,1] neg_hi:[0,0,1]
	v_pk_fma_f32 v[136:137], v[148:149], v[128:129], v[136:137] neg_lo:[0,0,1] neg_hi:[0,0,1]
	v_pk_fma_f32 v[138:139], v[148:149], v[130:131], v[138:139] neg_lo:[0,0,1] neg_hi:[0,0,1]
	v_cvt_pk_bf16_f32 v140, v132, v133
	v_cvt_pk_bf16_f32 v141, v134, v135
	v_cvt_pk_bf16_f32 v142, v136, v137
	v_cvt_pk_bf16_f32 v143, v138, v139
	v_lshl_add_u64 v[150:151], v[224:225], 0, s[70:71]
	s_add_u32 s70, s70, 0x1000
	global_store_dwordx4 v[150:151], v[140:143], off
	v_cndmask_b32_e64 v144, v84, v52, s[68:69]
	v_cndmask_b32_e64 v145, v85, v53, s[68:69]
	v_cndmask_b32_e64 v146, v86, v54, s[68:69]
	v_cndmask_b32_e64 v147, v87, v55, s[68:69]
	v_lshlrev_b32_e32 v132, 16, v144
	v_and_b32_e32 v133, 0xffff0000, v144
	v_lshlrev_b32_e32 v134, 16, v145
	v_and_b32_e32 v135, 0xffff0000, v145
	v_lshlrev_b32_e32 v136, 16, v146
	v_and_b32_e32 v137, 0xffff0000, v146
	v_lshlrev_b32_e32 v138, 16, v147
	v_and_b32_e32 v139, 0xffff0000, v147
	v_pk_add_f32 v[124:125], v[124:125], v[132:133] neg_lo:[0,1] neg_hi:[0,1]
	v_pk_add_f32 v[126:127], v[126:127], v[134:135] neg_lo:[0,1] neg_hi:[0,1]
	v_pk_add_f32 v[128:129], v[128:129], v[136:137] neg_lo:[0,1] neg_hi:[0,1]
	v_pk_add_f32 v[130:131], v[130:131], v[138:139] neg_lo:[0,1] neg_hi:[0,1]
	s_waitcnt vmcnt(15)
; __device__ __forceinline__ float bf_lo(unsigned w) { return __uint_as_float(w << 16); }
; __device__ __forceinline__ float bf_hi(unsigned w) { return __uint_as_float(w & 0xffff0000u); }
; __device__ __forceinline__ unsigned pk2(float lo, float hi) { return f2bf(lo) | (f2bf(hi) << 16); }
; template <int W> __device__ __forceinline__ void pool_item(const bfu* u, bfu* pooled, int tb) {
;     v4u r[W + 7];
; #pragma unroll
;     for (int j = 0; j < W + 7; ++j) { const int t = tb - (W - 1) + j; r[j] = (t >= 0) ? *(const v4u*)(u + (size_t)t * 1024) : (v4u){0u, 0u, 0u, 0u}; }
;     float a[8];
; #pragma unroll
;     for (int e = 0; e < 8; ++e) a[e] = 0.f;
;     ...
;     for (int k = 0; k < 8; ++k) {
;         const v4u c = r[W - 1 + k]; const int t = tb + k;
;         const float cv[8] = {pg8::bf_lo(c.x), pg8::bf_hi(c.x), pg8::bf_lo(c.y), pg8::bf_hi(c.y), pg8::bf_lo(c.z), pg8::bf_hi(c.z), pg8::bf_lo(c.w), pg8::bf_hi(c.w)};
; #pragma unroll
;         for (int e = 0; e < 8; ++e) a[e] += cv[e];
;         const float inv = 1.f / (float)((t + 1) < W ? (t + 1) : W);
;         v4u o; o.x = pk2(a[0] * inv - cv[0], a[1] * inv - cv[1]); o.y = pk2(a[2] * inv - cv[2], a[3] * inv - cv[3]); o.z = pk2(a[4] * inv - cv[4], a[5] * inv - cv[5]); o.w = pk2(a[6] * inv - cv[6], a[7] * inv - cv[7]);
;         *(v4u*)(pooled + (size_t)t * 2048) = o;
;         const v4u d = r[k];
;         a[0] -= pg8::bf_lo(d.x); a[1] -= pg8::bf_hi(d.x); a[2] -= pg8::bf_lo(d.y); a[3] -= pg8::bf_hi(d.y); a[4] -= pg8::bf_lo(d.z); a[5] -= pg8::bf_hi(d.z); a[6] -= pg8::bf_lo(d.w); a[7] -= pg8::bf_hi(d.w);
;     }
	v_lshlrev_b32_e32 v132, 16, v116
	v_and_b32_e32 v133, 0xffff0000, v116
	v_lshlrev_b32_e32 v134, 16, v117
	v_and_b32_e32 v135, 0xffff0000, v117
	v_lshlrev_b32_e32 v136, 16, v118
	v_and_b32_e32 v137, 0xffff0000, v118
	v_lshlrev_b32_e32 v138, 16, v119
	v_and_b32_e32 v139, 0xffff0000, v119
	v_pk_add_f32 v[124:125], v[124:125], v[132:133]
	v_pk_add_f32 v[126:127], v[126:127], v[134:135]
	v_pk_add_f32 v[128:129], v[128:129], v[136:137]
	v_pk_add_f32 v[130:131], v[130:131], v[138:139]
	v_pk_fma_f32 v[132:133], v[148:149], v[124:125], v[132:133] neg_lo:[0,0,1] neg_hi:[0,0,1]
	v_pk_fma_f32 v[134:135], v[148:149], v[126:127], v[134:135] neg_lo:[0,0,1] neg_hi:[0,0,1]
	v_pk_fma_f32 v[136:137], v[148:149], v[128:129], v[136:137] neg_lo:[0,0,1] neg_hi:[0,0,1]
	v_pk_fma_f32 v[138:139], v[148:149], v[130:131], v[138:139] neg_lo:[0,0,1] neg_hi:[0,0,1]
	v_cvt_pk_bf16_f32 v140, v132, v133
	v_cvt_pk_bf16_f32 v141, v134, v135
	v_cvt_pk_bf16_f32 v142, v136, v137
	v_cvt_pk_bf16_f32 v143, v138, v139
	v_lshl_add_u64 v[150:151], v[224:225], 0, s[70:71]
	s_add_u32 s70, s70, 0x1000
	global_store_dwordx4 v[150:151], v[140:143], off
	v_cndmask_b32_e64 v144, v88, v56, s[68:69]
	v_cndmask_b32_e64 v145, v89, v57, s[68:69]
	v_cndmask_b32_e64 v146, v90, v58, s[68:69]
	v_cndmask_b32_e64 v147, v91, v59, s[68:69]
	v_lshlrev_b32_e32 v132, 16, v144
	v_and_b32_e32 v133, 0xffff0000, v144
	v_lshlrev_b32_e32 v134, 16, v145
	v_and_b32_e32 v135, 0xffff0000, v145
	v_lshlrev_b32_e32 v136, 16, v146
	v_and_b32_e32 v137, 0xffff0000, v146
	v_lshlrev_b32_e32 v138, 16, v147
	v_and_b32_e32 v139, 0xffff0000, v147
	v_pk_add_f32 v[124:125], v[124:125], v[132:133] neg_lo:[0,1] neg_hi:[0,1]
	v_pk_add_f32 v[126:127], v[126:127], v[134:135] neg_lo:[0,1] neg_hi:[0,1]
	v_pk_add_f32 v[128:129], v[128:129], v[136:137] neg_lo:[0,1] neg_hi:[0,1]
	v_pk_add_f32 v[130:131], v[130:131], v[138:139] neg_lo:[0,1] neg_hi:[0,1]
	s_waitcnt vmcnt(15)
	v_lshlrev_b32_e32 v132, 16, v120
	v_and_b32_e32 v133, 0xffff0000, v120
	v_lshlrev_b32_e32 v134, 16, v121
	v_and_b32_e32 v135, 0xffff0000, v121
	v_lshlrev_b32_e32 v136, 16, v122
	v_and_b32_e32 v137, 0xffff0000, v122
	v_lshlrev_b32_e32 v138, 16, v123
	v_and_b32_e32 v139, 0xffff0000, v123
	v_pk_add_f32 v[124:125], v[124:125], v[132:133]
	v_pk_add_f32 v[126:127], v[126:127], v[134:135]
	v_pk_add_f32 v[128:129], v[128:129], v[136:137]
	v_pk_add_f32 v[130:131], v[130:131], v[138:139]
	v_pk_fma_f32 v[132:133], v[148:149], v[124:125], v[132:133] neg_lo:[0,0,1] neg_hi:[0,0,1]
	v_pk_fma_f32 v[134:135], v[148:149], v[126:127], v[134:135] neg_lo:[0,0,1] neg_hi:[0,0,1]
	v_pk_fma_f32 v[136:137], v[148:149], v[128:129], v[136:137] neg_lo:[0,0,1] neg_hi:[0,0,1]
	v_pk_fma_f32 v[138:139], v[148:149], v[130:131], v[138:139] neg_lo:[0,0,1] neg_hi:[0,0,1]
	v_cvt_pk_bf16_f32 v140, v132, v133
	v_cvt_pk_bf16_f32 v141, v134, v135
	v_cvt_pk_bf16_f32 v142, v136, v137
	v_cvt_pk_bf16_f32 v143, v138, v139
	v_lshl_add_u64 v[150:151], v[224:225], 0, s[70:71]
	s_add_u32 s70, s70, 0x1000
	global_store_dwordx4 v[150:151], v[140:143], off
	v_cndmask_b32_e64 v144, v92, v60, s[68:69]
	v_cndmask_b32_e64 v145, v93, v61, s[68:69]
	v_cndmask_b32_e64 v146, v94, v62, s[68:69]
	v_cndmask_b32_e64 v147, v95, v63, s[68:69]
	v_lshlrev_b32_e32 v132, 16, v144
	v_and_b32_e32 v133, 0xffff0000, v144
	v_lshlrev_b32_e32 v134, 16, v145
	v_and_b32_e32 v135, 0xffff0000, v145
	v_lshlrev_b32_e32 v136, 16, v146
	v_and_b32_e32 v137, 0xffff0000, v146
	v_lshlrev_b32_e32 v138, 16, v147
	v_and_b32_e32 v139, 0xffff0000, v147
	v_pk_add_f32 v[124:125], v[124:125], v[132:133] neg_lo:[0,1] neg_hi:[0,1]
	v_pk_add_f32 v[126:127], v[126:127], v[134:135] neg_lo:[0,1] neg_hi:[0,1]
	v_pk_add_f32 v[128:129], v[128:129], v[136:137] neg_lo:[0,1] neg_hi:[0,1]
	v_pk_add_f32 v[130:131], v[130:131], v[138:139] neg_lo:[0,1] neg_hi:[0,1]
	s_branch .Lpool_done
.Lpool_even:
	s_add_u32 s66, s66, 0x6000
	v_lshl_add_u64 v[48:49], v[222:223], 0, s[66:67]
	global_load_dwordx4 v[48:51], v[48:49], off
	s_add_u32 s66, s66, 0x800
	v_lshl_add_u64 v[52:53], v[222:223], 0, s[66:67]
	global_load_dwordx4 v[52:55], v[52:53], off
	s_add_u32 s66, s66, 0x800
	v_lshl_add_u64 v[56:57], v[222:223], 0, s[66:67]
	global_load_dwordx4 v[56:59], v[56:57], off
	s_add_u32 s66, s66, 0x800
	v_lshl_add_u64 v[60:61], v[222:223], 0, s[66:67]
	global_load_dwordx4 v[60:63], v[60:61], off
	s_add_u32 s66, s66, 0x800
	v_lshl_add_u64 v[64:65], v[222:223], 0, s[66:67]
	global_load_dwordx4 v[64:67], v[64:65], off
	s_add_u32 s66, s66, 0x800
	v_lshl_add_u64 v[68:69], v[222:223], 0, s[66:67]
	global_load_dwordx4 v[68:71], v[68:69], off
	s_add_u32 s66, s66, 0x800
	v_lshl_add_u64 v[72:73], v[222:223], 0, s[66:67]
	global_load_dwordx4 v[72:75], v[72:73], off
	s_add_u32 s66, s66, 0x800
	v_lshl_add_u64 v[76:77], v[222:223], 0, s[66:67]
	global_load_dwordx4 v[76:79], v[76:77], off
	s_add_u32 s66, s66, 0x800
	v_lshl_add_u64 v[80:81], v[222:223], 0, s[66:67]
	global_load_dwordx4 v[80:83], v[80:81], off
	s_add_u32 s66, s66, 0x800
	v_lshl_add_u64 v[84:85], v[222:223], 0, s[66:67]
	global_load_dwordx4 v[84:87], v[84:85], off
	s_add_u32 s66, s66, 0x800
	v_lshl_add_u64 v[88:89], v[222:223], 0, s[66:67]
	global_load_dwordx4 v[88:91], v[88:89], off
	s_add_u32 s66, s66, 0x800
	v_lshl_add_u64 v[92:93], v[222:223], 0, s[66:67]
	global_load_dwordx4 v[92:95], v[92:93], off
	s_add_u32 s66, s66, 0x800
	v_lshl_add_u64 v[96:97], v[222:223], 0, s[66:67]
	global_load_dwordx4 v[96:99], v[96:97], off
	s_add_u32 s66, s66, 0x800
	v_lshl_add_u64 v[100:101], v[222:223], 0, s[66:67]
	global_load_dwordx4 v[100:103], v[100:101], off
	s_add_u32 s66, s66, 0x800
	v_lshl_add_u64 v[104:105], v[222:223], 0, s[66:67]
	global_load_dwordx4 v[104:107], v[104:105], off
	s_add_u32 s66, s66, 0x800
	v_lshl_add_u64 v[108:109], v[222:223], 0, s[66:67]
	global_load_dwordx4 v[108:111], v[108:109], off
	s_add_u32 s66, s66, 0x800
	v_lshl_add_u64 v[112:113], v[222:223], 0, s[66:67]
	global_load_dwordx4 v[112:115], v[112:113], off
	s_add_u32 s66, s66, 0x800
	v_lshl_add_u64 v[116:117], v[222:223], 0, s[66:67]
	global_load_dwordx4 v[116:119], v[116:117], off
	s_add_u32 s66, s66, 0x800
	v_lshl_add_u64 v[120:121], v[222:223], 0, s[66:67]
	global_load_dwordx4 v[120:123], v[120:121], off
	s_add_u32 s66, s66, 0x800
	s_mov_b64 exec, -1
	v_mov_b32_e32 v148, 0x3f000000
	v_mov_b32_e32 v149, 0x3f000000
	v_mov_b32_e32 v124, 0
	v_mov_b32_e32 v125, 0
	v_mov_b32_e32 v126, 0
	v_mov_b32_e32 v127, 0
	v_mov_b32_e32 v128, 0
	v_mov_b32_e32 v129, 0
	v_mov_b32_e32 v130, 0
	v_mov_b32_e32 v131, 0
	s_mov_b64 exec, s[68:69]
	v_mov_b32_e32 v148, 0x3e800000
	v_mov_b32_e32 v149, 0x3e800000
	s_waitcnt vmcnt(18)
; __device__ __forceinline__ float bf_lo(unsigned w) { return __uint_as_float(w << 16); }
; __device__ __forceinline__ float bf_hi(unsigned w) { return __uint_as_float(w & 0xffff0000u); }
; __device__ __forceinline__ unsigned pk2(float lo, float hi) { return f2bf(lo) | (f2bf(hi) << 16); }
; template <int W> __device__ __forceinline__ void pool_item(const bfu* u, bfu* pooled, int tb) {
;     ...
; #pragma unroll
;     for (int j = 0; j < W - 1; ++j) { a[0] += pg8::bf_lo(r[j].x); a[1] += pg8::bf_hi(r[j].x); a[2] += pg8::bf_lo(r[j].y); a[3] += pg8::bf_hi(r[j].y); a[4] += pg8::bf_lo(r[j].z); a[5] += pg8::bf_hi(r[j].z); a[6] += pg8::bf_lo(r[j].w); a[7] += pg8::bf_hi(r[j].w); }
; #pragma unroll
;     for (int k = 0; k < 8; ++k) {
;         const v4u c = r[W - 1 + k]; const int t = tb + k;
;         const float cv[8] = {pg8::bf_lo(c.x), pg8::bf_hi(c.x), pg8::bf_lo(c.y), pg8::bf_hi(c.y), pg8::bf_lo(c.z), pg8::bf_hi(c.z), pg8::bf_lo(c.w), pg8::bf_hi(c.w)};
; #pragma unroll
;         for (int e = 0; e < 8; ++e) a[e] += cv[e];
;         const float inv = 1.f / (float)((t + 1) < W ? (t + 1) : W);
;         v4u o; o.x = pk2(a[0] * inv - cv[0], a[1] * inv - cv[1]); o.y = pk2(a[2] * inv - cv[2], a[3] * inv - cv[3]); o.z = pk2(a[4] * inv - cv[4], a[5] * inv - cv[5]); o.w = pk2(a[6] * inv - cv[6], a[7] * inv - cv[7]);
;         *(v4u*)(pooled + (size_t)t * 2048) = o;
;         const v4u d = r[k];
;         a[0] -= pg8::bf_lo(d.x); a[1] -= pg8::bf_hi(d.x); a[2] -= pg8::bf_lo(d.y); a[3] -= pg8::bf_hi(d.y); a[4] -= pg8::bf_lo(d.z); a[5] -= pg8::bf_hi(d.z); a[6] -= pg8::bf_lo(d.w); a[7] -= pg8::bf_hi(d.w);
;     }
	v_lshlrev_b32_e32 v132, 16, v48
	v_and_b32_e32 v133, 0xffff0000, v48
	v_lshlrev_b32_e32 v134, 16, v49
	v_and_b32_e32 v135, 0xffff0000, v49
	v_lshlrev_b32_e32 v136, 16, v50
	v_and_b32_e32 v137, 0xffff0000, v50
	v_lshlrev_b32_e32 v138, 16, v51
	v_and_b32_e32 v139, 0xffff0000, v51
	v_pk_add_f32 v[124:125], v[124:125], v[132:133]
	v_pk_add_f32 v[126:127], v[126:127], v[134:135]
	v_pk_add_f32 v[128:129], v[128:129], v[136:137]
	v_pk_add_f32 v[130:131], v[130:131], v[138:139]
	s_waitcnt vmcnt(17)
	v_lshlrev_b32_e32 v132, 16, v52
	v_and_b32_e32 v133, 0xffff0000, v52
	v_lshlrev_b32_e32 v134, 16, v53
	v_and_b32_e32 v135, 0xffff0000, v53
	v_lshlrev_b32_e32 v136, 16, v54
	v_and_b32_e32 v137, 0xffff0000, v54
	v_lshlrev_b32_e32 v138, 16, v55
	v_and_b32_e32 v139, 0xffff0000, v55
	v_pk_add_f32 v[124:125], v[124:125], v[132:133]
	v_pk_add_f32 v[126:127], v[126:127], v[134:135]
	v_pk_add_f32 v[128:129], v[128:129], v[136:137]
	v_pk_add_f32 v[130:131], v[130:131], v[138:139]
	s_mov_b64 exec, -1
	s_waitcnt vmcnt(16)
	v_lshlrev_b32_e32 v132, 16, v56
	v_and_b32_e32 v133, 0xffff0000, v56
	v_lshlrev_b32_e32 v134, 16, v57
	v_and_b32_e32 v135, 0xffff0000, v57
	v_lshlrev_b32_e32 v136, 16, v58
	v_and_b32_e32 v137, 0xffff0000, v58
	v_lshlrev_b32_e32 v138, 16, v59
	v_and_b32_e32 v139, 0xffff0000, v59
	v_pk_add_f32 v[124:125], v[124:125], v[132:133]
	v_pk_add_f32 v[126:127], v[126:127], v[134:135]
	v_pk_add_f32 v[128:129], v[128:129], v[136:137]
	v_pk_add_f32 v[130:131], v[130:131], v[138:139]
	s_waitcnt vmcnt(15)
	v_lshlrev_b32_e32 v132, 16, v60
	v_and_b32_e32 v133, 0xffff0000, v60
	v_lshlrev_b32_e32 v134, 16, v61
	v_and_b32_e32 v135, 0xffff0000, v61
	v_lshlrev_b32_e32 v136, 16, v62
	v_and_b32_e32 v137, 0xffff0000, v62
	v_lshlrev_b32_e32 v138, 16, v63
	v_and_b32_e32 v139, 0xffff0000, v63
	v_pk_add_f32 v[124:125], v[124:125], v[132:133]
	v_pk_add_f32 v[126:127], v[126:127], v[134:135]
	v_pk_add_f32 v[128:129], v[128:129], v[136:137]
	v_pk_add_f32 v[130:131], v[130:131], v[138:139]
	v_pk_fma_f32 v[132:133], v[148:149], v[124:125], v[132:133] neg_lo:[0,0,1] neg_hi:[0,0,1]
	v_pk_fma_f32 v[134:135], v[148:149], v[126:127], v[134:135] neg_lo:[0,0,1] neg_hi:[0,0,1]
	v_pk_fma_f32 v[136:137], v[148:149], v[128:129], v[136:137] neg_lo:[0,0,1] neg_hi:[0,0,1]
	v_pk_fma_f32 v[138:139], v[148:149], v[130:131], v[138:139] neg_lo:[0,0,1] neg_hi:[0,0,1]
	v_cvt_pk_bf16_f32 v140, v132, v133
	v_cvt_pk_bf16_f32 v141, v134, v135
	v_cvt_pk_bf16_f32 v142, v136, v137
	v_cvt_pk_bf16_f32 v143, v138, v139
	v_lshl_add_u64 v[150:151], v[224:225], 0, s[70:71]
	s_add_u32 s70, s70, 0x1000
	global_store_dwordx4 v[150:151], v[140:143], off
	v_cndmask_b32_e64 v144, v56, v48, s[68:69]
	v_cndmask_b32_e64 v145, v57, v49, s[68:69]
	v_cndmask_b32_e64 v146, v58, v50, s[68:69]
	v_cndmask_b32_e64 v147, v59, v51, s[68:69]
	v_lshlrev_b32_e32 v132, 16, v144
	v_and_b32_e32 v133, 0xffff0000, v144
	v_lshlrev_b32_e32 v134, 16, v145
	v_and_b32_e32 v135, 0xffff0000, v145
	v_lshlrev_b32_e32 v136, 16, v146
	v_and_b32_e32 v137, 0xffff0000, v146
	v_lshlrev_b32_e32 v138, 16, v147
	v_and_b32_e32 v139, 0xffff0000, v147
	v_pk_add_f32 v[124:125], v[124:125], v[132:133] neg_lo:[0,1] neg_hi:[0,1]
	v_pk_add_f32 v[126:127], v[126:127], v[134:135] neg_lo:[0,1] neg_hi:[0,1]
	v_pk_add_f32 v[128:129], v[128:129], v[136:137] neg_lo:[0,1] neg_hi:[0,1]
	v_pk_add_f32 v[130:131], v[130:131], v[138:139] neg_lo:[0,1] neg_hi:[0,1]
	s_waitcnt vmcnt(15)
	v_lshlrev_b32_e32 v132, 16, v64
	v_and_b32_e32 v133, 0xffff0000, v64
	v_lshlrev_b32_e32 v134, 16, v65
	v_and_b32_e32 v135, 0xffff0000, v65
	v_lshlrev_b32_e32 v136, 16, v66
	v_and_b32_e32 v137, 0xffff0000, v66
	v_lshlrev_b32_e32 v138, 16, v67
	v_and_b32_e32 v139, 0xffff0000, v67
	v_pk_add_f32 v[124:125], v[124:125], v[132:133]
	v_pk_add_f32 v[126:127], v[126:127], v[134:135]
	v_pk_add_f32 v[128:129], v[128:129], v[136:137]
	v_pk_add_f32 v[130:131], v[130:131], v[138:139]
	v_pk_fma_f32 v[132:133], v[148:149], v[124:125], v[132:133] neg_lo:[0,0,1] neg_hi:[0,0,1]
	v_pk_fma_f32 v[134:135], v[148:149], v[126:127], v[134:135] neg_lo:[0,0,1] neg_hi:[0,0,1]
	v_pk_fma_f32 v[136:137], v[148:149], v[128:129], v[136:137] neg_lo:[0,0,1] neg_hi:[0,0,1]
	v_pk_fma_f32 v[138:139], v[148:149], v[130:131], v[138:139] neg_lo:[0,0,1] neg_hi:[0,0,1]
	v_cvt_pk_bf16_f32 v140, v132, v133
	v_cvt_pk_bf16_f32 v141, v134, v135
	v_cvt_pk_bf16_f32 v142, v136, v137
	v_cvt_pk_bf16_f32 v143, v138, v139
	v_lshl_add_u64 v[150:151], v[224:225], 0, s[70:71]
	s_add_u32 s70, s70, 0x1000
	global_store_dwordx4 v[150:151], v[140:143], off
	v_cndmask_b32_e64 v144, v60, v52, s[68:69]
	v_cndmask_b32_e64 v145, v61, v53, s[68:69]
	v_cndmask_b32_e64 v146, v62, v54, s[68:69]
	v_cndmask_b32_e64 v147, v63, v55, s[68:69]
	v_lshlrev_b32_e32 v132, 16, v144
	v_and_b32_e32 v133, 0xffff0000, v144
	v_lshlrev_b32_e32 v134, 16, v145
	v_and_b32_e32 v135, 0xffff0000, v145
	v_lshlrev_b32_e32 v136, 16, v146
	v_and_b32_e32 v137, 0xffff0000, v146
	v_lshlrev_b32_e32 v138, 16, v147
	v_and_b32_e32 v139, 0xffff0000, v147
	v_pk_add_f32 v[124:125], v[124:125], v[132:133] neg_lo:[0,1] neg_hi:[0,1]
	v_pk_add_f32 v[126:127], v[126:127], v[134:135] neg_lo:[0,1] neg_hi:[0,1]
	v_pk_add_f32 v[128:129], v[128:129], v[136:137] neg_lo:[0,1] neg_hi:[0,1]
	v_pk_add_f32 v[130:131], v[130:131], v[138:139] neg_lo:[0,1] neg_hi:[0,1]
	s_waitcnt vmcnt(15)
; __device__ __forceinline__ float bf_lo(unsigned w) { return __uint_as_float(w << 16); }
; __device__ __forceinline__ float bf_hi(unsigned w) { return __uint_as_float(w & 0xffff0000u); }
; __device__ __forceinline__ unsigned pk2(float lo, float hi) { return f2bf(lo) | (f2bf(hi) << 16); }
; template <int W> __device__ __forceinline__ void pool_item(const bfu* u, bfu* pooled, int tb) {
;     ...
;     for (int k = 0; k < 8; ++k) {
;         const v4u c = r[W - 1 + k]; const int t = tb + k;
;         const float cv[8] = {pg8::bf_lo(c.x), pg8::bf_hi(c.x), pg8::bf_lo(c.y), pg8::bf_hi(c.y), pg8::bf_lo(c.z), pg8::bf_hi(c.z), pg8::bf_lo(c.w), pg8::bf_hi(c.w)};
; #pragma unroll
;         for (int e = 0; e < 8; ++e) a[e] += cv[e];
;         const float inv = 1.f / (float)((t + 1) < W ? (t + 1) : W);
;         v4u o; o.x = pk2(a[0] * inv - cv[0], a[1] * inv - cv[1]); o.y = pk2(a[2] * inv - cv[2], a[3] * inv - cv[3]); o.z = pk2(a[4] * inv - cv[4], a[5] * inv - cv[5]); o.w = pk2(a[6] * inv - cv[6], a[7] * inv - cv[7]);
;         *(v4u*)(pooled + (size_t)t * 2048) = o;
;         const v4u d = r[k];
;         a[0] -= pg8::bf_lo(d.x); a[1] -= pg8::bf_hi(d.x); a[2] -= pg8::bf_lo(d.y); a[3] -= pg8::bf_hi(d.y); a[4] -= pg8::bf_lo(d.z); a[5] -= pg8::bf_hi(d.z); a[6] -= pg8::bf_lo(d.w); a[7] -= pg8::bf_hi(d.w);
;     }
	v_lshlrev_b32_e32 v132, 16, v68
	v_and_b32_e32 v133, 0xffff0000, v68
	v_lshlrev_b32_e32 v134, 16, v69
	v_and_b32_e32 v135, 0xffff0000, v69
	v_lshlrev_b32_e32 v136, 16, v70
	v_and_b32_e32 v137, 0xffff0000, v70
	v_lshlrev_b32_e32 v138, 16, v71
	v_and_b32_e32 v139, 0xffff0000, v71
	v_pk_add_f32 v[124:125], v[124:125], v[132:133]
	v_pk_add_f32 v[126:127], v[126:127], v[134:135]
	v_pk_add_f32 v[128:129], v[128:129], v[136:137]
	v_pk_add_f32 v[130:131], v[130:131], v[138:139]
	v_pk_fma_f32 v[132:133], v[148:149], v[124:125], v[132:133] neg_lo:[0,0,1] neg_hi:[0,0,1]
	v_pk_fma_f32 v[134:135], v[148:149], v[126:127], v[134:135] neg_lo:[0,0,1] neg_hi:[0,0,1]
	v_pk_fma_f32 v[136:137], v[148:149], v[128:129], v[136:137] neg_lo:[0,0,1] neg_hi:[0,0,1]
	v_pk_fma_f32 v[138:139], v[148:149], v[130:131], v[138:139] neg_lo:[0,0,1] neg_hi:[0,0,1]
	v_cvt_pk_bf16_f32 v140, v132, v133
	v_cvt_pk_bf16_f32 v141, v134, v135
	v_cvt_pk_bf16_f32 v142, v136, v137
	v_cvt_pk_bf16_f32 v143, v138, v139
	v_lshl_add_u64 v[150:151], v[224:225], 0, s[70:71]
	s_add_u32 s70, s70, 0x1000
	global_store_dwordx4 v[150:151], v[140:143], off
	v_cndmask_b32_e64 v144, v64, v56, s[68:69]
	v_cndmask_b32_e64 v145, v65, v57, s[68:69]
	v_cndmask_b32_e64 v146, v66, v58, s[68:69]
	v_cndmask_b32_e64 v147, v67, v59, s[68:69]
	v_lshlrev_b32_e32 v132, 16, v144
	v_and_b32_e32 v133, 0xffff0000, v144
	v_lshlrev_b32_e32 v134, 16, v145
	v_and_b32_e32 v135, 0xffff0000, v145
	v_lshlrev_b32_e32 v136, 16, v146
	v_and_b32_e32 v137, 0xffff0000, v146
	v_lshlrev_b32_e32 v138, 16, v147
	v_and_b32_e32 v139, 0xffff0000, v147
	v_pk_add_f32 v[124:125], v[124:125], v[132:133] neg_lo:[0,1] neg_hi:[0,1]
	v_pk_add_f32 v[126:127], v[126:127], v[134:135] neg_lo:[0,1] neg_hi:[0,1]
	v_pk_add_f32 v[128:129], v[128:129], v[136:137] neg_lo:[0,1] neg_hi:[0,1]
	v_pk_add_f32 v[130:131], v[130:131], v[138:139] neg_lo:[0,1] neg_hi:[0,1]
	s_waitcnt vmcnt(15)
	v_lshlrev_b32_e32 v132, 16, v72
	v_and_b32_e32 v133, 0xffff0000, v72
	v_lshlrev_b32_e32 v134, 16, v73
	v_and_b32_e32 v135, 0xffff0000, v73
	v_lshlrev_b32_e32 v136, 16, v74
	v_and_b32_e32 v137, 0xffff0000, v74
	v_lshlrev_b32_e32 v138, 16, v75
	v_and_b32_e32 v139, 0xffff0000, v75
	v_pk_add_f32 v[124:125], v[124:125], v[132:133]
	v_pk_add_f32 v[126:127], v[126:127], v[134:135]
	v_pk_add_f32 v[128:129], v[128:129], v[136:137]
	v_pk_add_f32 v[130:131], v[130:131], v[138:139]
	v_pk_fma_f32 v[132:133], v[148:149], v[124:125], v[132:133] neg_lo:[0,0,1] neg_hi:[0,0,1]
	v_pk_fma_f32 v[134:135], v[148:149], v[126:127], v[134:135] neg_lo:[0,0,1] neg_hi:[0,0,1]
	v_pk_fma_f32 v[136:137], v[148:149], v[128:129], v[136:137] neg_lo:[0,0,1] neg_hi:[0,0,1]
	v_pk_fma_f32 v[138:139], v[148:149], v[130:131], v[138:139] neg_lo:[0,0,1] neg_hi:[0,0,1]
	v_cvt_pk_bf16_f32 v140, v132, v133
	v_cvt_pk_bf16_f32 v141, v134, v135
	v_cvt_pk_bf16_f32 v142, v136, v137
	v_cvt_pk_bf16_f32 v143, v138, v139
	v_lshl_add_u64 v[150:151], v[224:225], 0, s[70:71]
	s_add_u32 s70, s70, 0x1000
	global_store_dwordx4 v[150:151], v[140:143], off
	v_cndmask_b32_e64 v144, v68, v60, s[68:69]
	v_cndmask_b32_e64 v145, v69, v61, s[68:69]
	v_cndmask_b32_e64 v146, v70, v62, s[68:69]
	v_cndmask_b32_e64 v147, v71, v63, s[68:69]
	v_lshlrev_b32_e32 v132, 16, v144
	v_and_b32_e32 v133, 0xffff0000, v144
	v_lshlrev_b32_e32 v134, 16, v145
	v_and_b32_e32 v135, 0xffff0000, v145
	v_lshlrev_b32_e32 v136, 16, v146
	v_and_b32_e32 v137, 0xffff0000, v146
	v_lshlrev_b32_e32 v138, 16, v147
	v_and_b32_e32 v139, 0xffff0000, v147
	v_pk_add_f32 v[124:125], v[124:125], v[132:133] neg_lo:[0,1] neg_hi:[0,1]
	v_pk_add_f32 v[126:127], v[126:127], v[134:135] neg_lo:[0,1] neg_hi:[0,1]
	v_pk_add_f32 v[128:129], v[128:129], v[136:137] neg_lo:[0,1] neg_hi:[0,1]
	v_pk_add_f32 v[130:131], v[130:131], v[138:139] neg_lo:[0,1] neg_hi:[0,1]
	s_waitcnt vmcnt(15)
	v_lshlrev_b32_e32 v132, 16, v76
	v_and_b32_e32 v133, 0xffff0000, v76
	v_lshlrev_b32_e32 v134, 16, v77
	v_and_b32_e32 v135, 0xffff0000, v77
	v_lshlrev_b32_e32 v136, 16, v78
	v_and_b32_e32 v137, 0xffff0000, v78
	v_lshlrev_b32_e32 v138, 16, v79
	v_and_b32_e32 v139, 0xffff0000, v79
	v_pk_add_f32 v[124:125], v[124:125], v[132:133]
	v_pk_add_f32 v[126:127], v[126:127], v[134:135]
	v_pk_add_f32 v[128:129], v[128:129], v[136:137]
	v_pk_add_f32 v[130:131], v[130:131], v[138:139]
	v_pk_fma_f32 v[132:133], v[148:149], v[124:125], v[132:133] neg_lo:[0,0,1] neg_hi:[0,0,1]
	v_pk_fma_f32 v[134:135], v[148:149], v[126:127], v[134:135] neg_lo:[0,0,1] neg_hi:[0,0,1]
	v_pk_fma_f32 v[136:137], v[148:149], v[128:129], v[136:137] neg_lo:[0,0,1] neg_hi:[0,0,1]
	v_pk_fma_f32 v[138:139], v[148:149], v[130:131], v[138:139] neg_lo:[0,0,1] neg_hi:[0,0,1]
	v_cvt_pk_bf16_f32 v140, v132, v133
	v_cvt_pk_bf16_f32 v141, v134, v135
	v_cvt_pk_bf16_f32 v142, v136, v137
	v_cvt_pk_bf16_f32 v143, v138, v139
	v_lshl_add_u64 v[150:151], v[224:225], 0, s[70:71]
	s_add_u32 s70, s70, 0x1000
	global_store_dwordx4 v[150:151], v[140:143], off
	v_cndmask_b32_e64 v144, v72, v64, s[68:69]
	v_cndmask_b32_e64 v145, v73, v65, s[68:69]
	v_cndmask_b32_e64 v146, v74, v66, s[68:69]
	v_cndmask_b32_e64 v147, v75, v67, s[68:69]
	v_lshlrev_b32_e32 v132, 16, v144
	v_and_b32_e32 v133, 0xffff0000, v144
	v_lshlrev_b32_e32 v134, 16, v145
	v_and_b32_e32 v135, 0xffff0000, v145
	v_lshlrev_b32_e32 v136, 16, v146
	v_and_b32_e32 v137, 0xffff0000, v146
	v_lshlrev_b32_e32 v138, 16, v147
	v_and_b32_e32 v139, 0xffff0000, v147
	v_pk_add_f32 v[124:125], v[124:125], v[132:133] neg_lo:[0,1] neg_hi:[0,1]
	v_pk_add_f32 v[126:127], v[126:127], v[134:135] neg_lo:[0,1] neg_hi:[0,1]
	v_pk_add_f32 v[128:129], v[128:129], v[136:137] neg_lo:[0,1] neg_hi:[0,1]
	v_pk_add_f32 v[130:131], v[130:131], v[138:139] neg_lo:[0,1] neg_hi:[0,1]
	s_waitcnt vmcnt(15)
; __device__ __forceinline__ float bf_lo(unsigned w) { return __uint_as_float(w << 16); }
; __device__ __forceinline__ float bf_hi(unsigned w) { return __uint_as_float(w & 0xffff0000u); }
; __device__ __forceinline__ unsigned pk2(float lo, float hi) { return f2bf(lo) | (f2bf(hi) << 16); }
; template <int W> __device__ __forceinline__ void pool_item(const bfu* u, bfu* pooled, int tb) {
;     ...
;     for (int k = 0; k < 8; ++k) {
;         const v4u c = r[W - 1 + k]; const int t = tb + k;
;         const float cv[8] = {pg8::bf_lo(c.x), pg8::bf_hi(c.x), pg8::bf_lo(c.y), pg8::bf_hi(c.y), pg8::bf_lo(c.z), pg8::bf_hi(c.z), pg8::bf_lo(c.w), pg8::bf_hi(c.w)};
; #pragma unroll
;         for (int e = 0; e < 8; ++e) a[e] += cv[e];
;         const float inv = 1.f / (float)((t + 1) < W ? (t + 1) : W);
;         v4u o; o.x = pk2(a[0] * inv - cv[0], a[1] * inv - cv[1]); o.y = pk2(a[2] * inv - cv[2], a[3] * inv - cv[3]); o.z = pk2(a[4] * inv - cv[4], a[5] * inv - cv[5]); o.w = pk2(a[6] * inv - cv[6], a[7] * inv - cv[7]);
;         *(v4u*)(pooled + (size_t)t * 2048) = o;
;         const v4u d = r[k];
;         a[0] -= pg8::bf_lo(d.x); a[1] -= pg8::bf_hi(d.x); a[2] -= pg8::bf_lo(d.y); a[3] -= pg8::bf_hi(d.y); a[4] -= pg8::bf_lo(d.z); a[5] -= pg8::bf_hi(d.z); a[6] -= pg8::bf_lo(d.w); a[7] -= pg8::bf_hi(d.w);
;     }
	v_lshlrev_b32_e32 v132, 16, v80
	v_and_b32_e32 v133, 0xffff0000, v80
	v_lshlrev_b32_e32 v134, 16, v81
	v_and_b32_e32 v135, 0xffff0000, v81
	v_lshlrev_b32_e32 v136, 16, v82
	v_and_b32_e32 v137, 0xffff0000, v82
	v_lshlrev_b32_e32 v138, 16, v83
	v_and_b32_e32 v139, 0xffff0000, v83
	v_pk_add_f32 v[124:125], v[124:125], v[132:133]
	v_pk_add_f32 v[126:127], v[126:127], v[134:135]
	v_pk_add_f32 v[128:129], v[128:129], v[136:137]
	v_pk_add_f32 v[130:131], v[130:131], v[138:139]
	v_pk_fma_f32 v[132:133], v[148:149], v[124:125], v[132:133] neg_lo:[0,0,1] neg_hi:[0,0,1]
	v_pk_fma_f32 v[134:135], v[148:149], v[126:127], v[134:135] neg_lo:[0,0,1] neg_hi:[0,0,1]
	v_pk_fma_f32 v[136:137], v[148:149], v[128:129], v[136:137] neg_lo:[0,0,1] neg_hi:[0,0,1]
	v_pk_fma_f32 v[138:139], v[148:149], v[130:131], v[138:139] neg_lo:[0,0,1] neg_hi:[0,0,1]
	v_cvt_pk_bf16_f32 v140, v132, v133
	v_cvt_pk_bf16_f32 v141, v134, v135
	v_cvt_pk_bf16_f32 v142, v136, v137
	v_cvt_pk_bf16_f32 v143, v138, v139
	v_lshl_add_u64 v[150:151], v[224:225], 0, s[70:71]
	s_add_u32 s70, s70, 0x1000
	global_store_dwordx4 v[150:151], v[140:143], off
	v_cndmask_b32_e64 v144, v76, v68, s[68:69]
	v_cndmask_b32_e64 v145, v77, v69, s[68:69]
	v_cndmask_b32_e64 v146, v78, v70, s[68:69]
	v_cndmask_b32_e64 v147, v79, v71, s[68:69]
	v_lshlrev_b32_e32 v132, 16, v144
	v_and_b32_e32 v133, 0xffff0000, v144
	v_lshlrev_b32_e32 v134, 16, v145
	v_and_b32_e32 v135, 0xffff0000, v145
	v_lshlrev_b32_e32 v136, 16, v146
	v_and_b32_e32 v137, 0xffff0000, v146
	v_lshlrev_b32_e32 v138, 16, v147
	v_and_b32_e32 v139, 0xffff0000, v147
	v_pk_add_f32 v[124:125], v[124:125], v[132:133] neg_lo:[0,1] neg_hi:[0,1]
	v_pk_add_f32 v[126:127], v[126:127], v[134:135] neg_lo:[0,1] neg_hi:[0,1]
	v_pk_add_f32 v[128:129], v[128:129], v[136:137] neg_lo:[0,1] neg_hi:[0,1]
	v_pk_add_f32 v[130:131], v[130:131], v[138:139] neg_lo:[0,1] neg_hi:[0,1]
	s_waitcnt vmcnt(15)
	v_lshlrev_b32_e32 v132, 16, v84
	v_and_b32_e32 v133, 0xffff0000, v84
	v_lshlrev_b32_e32 v134, 16, v85
	v_and_b32_e32 v135, 0xffff0000, v85
	v_lshlrev_b32_e32 v136, 16, v86
	v_and_b32_e32 v137, 0xffff0000, v86
	v_lshlrev_b32_e32 v138, 16, v87
	v_and_b32_e32 v139, 0xffff0000, v87
	v_pk_add_f32 v[124:125], v[124:125], v[132:133]
	v_pk_add_f32 v[126:127], v[126:127], v[134:135]
	v_pk_add_f32 v[128:129], v[128:129], v[136:137]
	v_pk_add_f32 v[130:131], v[130:131], v[138:139]
	v_pk_fma_f32 v[132:133], v[148:149], v[124:125], v[132:133] neg_lo:[0,0,1] neg_hi:[0,0,1]
	v_pk_fma_f32 v[134:135], v[148:149], v[126:127], v[134:135] neg_lo:[0,0,1] neg_hi:[0,0,1]
	v_pk_fma_f32 v[136:137], v[148:149], v[128:129], v[136:137] neg_lo:[0,0,1] neg_hi:[0,0,1]
	v_pk_fma_f32 v[138:139], v[148:149], v[130:131], v[138:139] neg_lo:[0,0,1] neg_hi:[0,0,1]
	v_cvt_pk_bf16_f32 v140, v132, v133
	v_cvt_pk_bf16_f32 v141, v134, v135
	v_cvt_pk_bf16_f32 v142, v136, v137
	v_cvt_pk_bf16_f32 v143, v138, v139
	v_lshl_add_u64 v[150:151], v[224:225], 0, s[70:71]
	s_add_u32 s70, s70, 0x1000
	global_store_dwordx4 v[150:151], v[140:143], off
	v_cndmask_b32_e64 v144, v80, v72, s[68:69]
	v_cndmask_b32_e64 v145, v81, v73, s[68:69]
	v_cndmask_b32_e64 v146, v82, v74, s[68:69]
	v_cndmask_b32_e64 v147, v83, v75, s[68:69]
	v_lshlrev_b32_e32 v132, 16, v144
	v_and_b32_e32 v133, 0xffff0000, v144
	v_lshlrev_b32_e32 v134, 16, v145
	v_and_b32_e32 v135, 0xffff0000, v145
	v_lshlrev_b32_e32 v136, 16, v146
	v_and_b32_e32 v137, 0xffff0000, v146
	v_lshlrev_b32_e32 v138, 16, v147
	v_and_b32_e32 v139, 0xffff0000, v147
	v_pk_add_f32 v[124:125], v[124:125], v[132:133] neg_lo:[0,1] neg_hi:[0,1]
	v_pk_add_f32 v[126:127], v[126:127], v[134:135] neg_lo:[0,1] neg_hi:[0,1]
	v_pk_add_f32 v[128:129], v[128:129], v[136:137] neg_lo:[0,1] neg_hi:[0,1]
	v_pk_add_f32 v[130:131], v[130:131], v[138:139] neg_lo:[0,1] neg_hi:[0,1]
	s_waitcnt vmcnt(15)
	v_lshlrev_b32_e32 v132, 16, v88
	v_and_b32_e32 v133, 0xffff0000, v88
	v_lshlrev_b32_e32 v134, 16, v89
	v_and_b32_e32 v135, 0xffff0000, v89
	v_lshlrev_b32_e32 v136, 16, v90
	v_and_b32_e32 v137, 0xffff0000, v90
	v_lshlrev_b32_e32 v138, 16, v91
	v_and_b32_e32 v139, 0xffff0000, v91
	v_pk_add_f32 v[124:125], v[124:125], v[132:133]
	v_pk_add_f32 v[126:127], v[126:127], v[134:135]
	v_pk_add_f32 v[128:129], v[128:129], v[136:137]
	v_pk_add_f32 v[130:131], v[130:131], v[138:139]
	v_pk_fma_f32 v[132:133], v[148:149], v[124:125], v[132:133] neg_lo:[0,0,1] neg_hi:[0,0,1]
	v_pk_fma_f32 v[134:135], v[148:149], v[126:127], v[134:135] neg_lo:[0,0,1] neg_hi:[0,0,1]
	v_pk_fma_f32 v[136:137], v[148:149], v[128:129], v[136:137] neg_lo:[0,0,1] neg_hi:[0,0,1]
	v_pk_fma_f32 v[138:139], v[148:149], v[130:131], v[138:139] neg_lo:[0,0,1] neg_hi:[0,0,1]
	v_cvt_pk_bf16_f32 v140, v132, v133
	v_cvt_pk_bf16_f32 v141, v134, v135
	v_cvt_pk_bf16_f32 v142, v136, v137
	v_cvt_pk_bf16_f32 v143, v138, v139
	v_lshl_add_u64 v[150:151], v[224:225], 0, s[70:71]
	s_add_u32 s70, s70, 0x1000
	global_store_dwordx4 v[150:151], v[140:143], off
	v_cndmask_b32_e64 v144, v84, v76, s[68:69]
	v_cndmask_b32_e64 v145, v85, v77, s[68:69]
	v_cndmask_b32_e64 v146, v86, v78, s[68:69]
	v_cndmask_b32_e64 v147, v87, v79, s[68:69]
	v_lshlrev_b32_e32 v132, 16, v144
	v_and_b32_e32 v133, 0xffff0000, v144
	v_lshlrev_b32_e32 v134, 16, v145
	v_and_b32_e32 v135, 0xffff0000, v145
	v_lshlrev_b32_e32 v136, 16, v146
	v_and_b32_e32 v137, 0xffff0000, v146
	v_lshlrev_b32_e32 v138, 16, v147
	v_and_b32_e32 v139, 0xffff0000, v147
	v_pk_add_f32 v[124:125], v[124:125], v[132:133] neg_lo:[0,1] neg_hi:[0,1]
	v_pk_add_f32 v[126:127], v[126:127], v[134:135] neg_lo:[0,1] neg_hi:[0,1]
	v_pk_add_f32 v[128:129], v[128:129], v[136:137] neg_lo:[0,1] neg_hi:[0,1]
	v_pk_add_f32 v[130:131], v[130:131], v[138:139] neg_lo:[0,1] neg_hi:[0,1]
	s_waitcnt vmcnt(15)
; __device__ __forceinline__ float bf_lo(unsigned w) { return __uint_as_float(w << 16); }
; __device__ __forceinline__ float bf_hi(unsigned w) { return __uint_as_float(w & 0xffff0000u); }
; __device__ __forceinline__ unsigned pk2(float lo, float hi) { return f2bf(lo) | (f2bf(hi) << 16); }
; template <int W> __device__ __forceinline__ void pool_item(const bfu* u, bfu* pooled, int tb) {
;     ...
;     for (int k = 0; k < 8; ++k) {
;         const v4u c = r[W - 1 + k]; const int t = tb + k;
;         const float cv[8] = {pg8::bf_lo(c.x), pg8::bf_hi(c.x), pg8::bf_lo(c.y), pg8::bf_hi(c.y), pg8::bf_lo(c.z), pg8::bf_hi(c.z), pg8::bf_lo(c.w), pg8::bf_hi(c.w)};
; #pragma unroll
;         for (int e = 0; e < 8; ++e) a[e] += cv[e];
;         const float inv = 1.f / (float)((t + 1) < W ? (t + 1) : W);
;         v4u o; o.x = pk2(a[0] * inv - cv[0], a[1] * inv - cv[1]); o.y = pk2(a[2] * inv - cv[2], a[3] * inv - cv[3]); o.z = pk2(a[4] * inv - cv[4], a[5] * inv - cv[5]); o.w = pk2(a[6] * inv - cv[6], a[7] * inv - cv[7]);
;         *(v4u*)(pooled + (size_t)t * 2048) = o;
;         const v4u d = r[k];
;         a[0] -= pg8::bf_lo(d.x); a[1] -= pg8::bf_hi(d.x); a[2] -= pg8::bf_lo(d.y); a[3] -= pg8::bf_hi(d.y); a[4] -= pg8::bf_lo(d.z); a[5] -= pg8::bf_hi(d.z); a[6] -= pg8::bf_lo(d.w); a[7] -= pg8::bf_hi(d.w);
;     }
	v_lshlrev_b32_e32 v132, 16, v92
	v_and_b32_e32 v133, 0xffff0000, v92
	v_lshlrev_b32_e32 v134, 16, v93
	v_and_b32_e32 v135, 0xffff0000, v93
	v_lshlrev_b32_e32 v136, 16, v94
	v_and_b32_e32 v137, 0xffff0000, v94
	v_lshlrev_b32_e32 v138, 16, v95
	v_and_b32_e32 v139, 0xffff0000, v95
	v_pk_add_f32 v[124:125], v[124:125], v[132:133]
	v_pk_add_f32 v[126:127], v[126:127], v[134:135]
	v_pk_add_f32 v[128:129], v[128:129], v[136:137]
	v_pk_add_f32 v[130:131], v[130:131], v[138:139]
	v_pk_fma_f32 v[132:133], v[148:149], v[124:125], v[132:133] neg_lo:[0,0,1] neg_hi:[0,0,1]
	v_pk_fma_f32 v[134:135], v[148:149], v[126:127], v[134:135] neg_lo:[0,0,1] neg_hi:[0,0,1]
	v_pk_fma_f32 v[136:137], v[148:149], v[128:129], v[136:137] neg_lo:[0,0,1] neg_hi:[0,0,1]
	v_pk_fma_f32 v[138:139], v[148:149], v[130:131], v[138:139] neg_lo:[0,0,1] neg_hi:[0,0,1]
	v_cvt_pk_bf16_f32 v140, v132, v133
	v_cvt_pk_bf16_f32 v141, v134, v135
	v_cvt_pk_bf16_f32 v142, v136, v137
	v_cvt_pk_bf16_f32 v143, v138, v139
	v_lshl_add_u64 v[150:151], v[224:225], 0, s[70:71]
	s_add_u32 s70, s70, 0x1000
	global_store_dwordx4 v[150:151], v[140:143], off
	v_cndmask_b32_e64 v144, v88, v80, s[68:69]
	v_cndmask_b32_e64 v145, v89, v81, s[68:69]
	v_cndmask_b32_e64 v146, v90, v82, s[68:69]
	v_cndmask_b32_e64 v147, v91, v83, s[68:69]
	v_lshlrev_b32_e32 v132, 16, v144
	v_and_b32_e32 v133, 0xffff0000, v144
	v_lshlrev_b32_e32 v134, 16, v145
	v_and_b32_e32 v135, 0xffff0000, v145
	v_lshlrev_b32_e32 v136, 16, v146
	v_and_b32_e32 v137, 0xffff0000, v146
	v_lshlrev_b32_e32 v138, 16, v147
	v_and_b32_e32 v139, 0xffff0000, v147
	v_pk_add_f32 v[124:125], v[124:125], v[132:133] neg_lo:[0,1] neg_hi:[0,1]
	v_pk_add_f32 v[126:127], v[126:127], v[134:135] neg_lo:[0,1] neg_hi:[0,1]
	v_pk_add_f32 v[128:129], v[128:129], v[136:137] neg_lo:[0,1] neg_hi:[0,1]
	v_pk_add_f32 v[130:131], v[130:131], v[138:139] neg_lo:[0,1] neg_hi:[0,1]
	s_waitcnt vmcnt(15)
	v_lshlrev_b32_e32 v132, 16, v96
	v_and_b32_e32 v133, 0xffff0000, v96
	v_lshlrev_b32_e32 v134, 16, v97
	v_and_b32_e32 v135, 0xffff0000, v97
	v_lshlrev_b32_e32 v136, 16, v98
	v_and_b32_e32 v137, 0xffff0000, v98
	v_lshlrev_b32_e32 v138, 16, v99
	v_and_b32_e32 v139, 0xffff0000, v99
	v_pk_add_f32 v[124:125], v[124:125], v[132:133]
	v_pk_add_f32 v[126:127], v[126:127], v[134:135]
	v_pk_add_f32 v[128:129], v[128:129], v[136:137]
	v_pk_add_f32 v[130:131], v[130:131], v[138:139]
	v_pk_fma_f32 v[132:133], v[148:149], v[124:125], v[132:133] neg_lo:[0,0,1] neg_hi:[0,0,1]
	v_pk_fma_f32 v[134:135], v[148:149], v[126:127], v[134:135] neg_lo:[0,0,1] neg_hi:[0,0,1]
	v_pk_fma_f32 v[136:137], v[148:149], v[128:129], v[136:137] neg_lo:[0,0,1] neg_hi:[0,0,1]
	v_pk_fma_f32 v[138:139], v[148:149], v[130:131], v[138:139] neg_lo:[0,0,1] neg_hi:[0,0,1]
	v_cvt_pk_bf16_f32 v140, v132, v133
	v_cvt_pk_bf16_f32 v141, v134, v135
	v_cvt_pk_bf16_f32 v142, v136, v137
	v_cvt_pk_bf16_f32 v143, v138, v139
	v_lshl_add_u64 v[150:151], v[224:225], 0, s[70:71]
	s_add_u32 s70, s70, 0x1000
	global_store_dwordx4 v[150:151], v[140:143], off
	v_cndmask_b32_e64 v144, v92, v84, s[68:69]
	v_cndmask_b32_e64 v145, v93, v85, s[68:69]
	v_cndmask_b32_e64 v146, v94, v86, s[68:69]
	v_cndmask_b32_e64 v147, v95, v87, s[68:69]
	v_lshlrev_b32_e32 v132, 16, v144
	v_and_b32_e32 v133, 0xffff0000, v144
	v_lshlrev_b32_e32 v134, 16, v145
	v_and_b32_e32 v135, 0xffff0000, v145
	v_lshlrev_b32_e32 v136, 16, v146
	v_and_b32_e32 v137, 0xffff0000, v146
	v_lshlrev_b32_e32 v138, 16, v147
	v_and_b32_e32 v139, 0xffff0000, v147
	v_pk_add_f32 v[124:125], v[124:125], v[132:133] neg_lo:[0,1] neg_hi:[0,1]
	v_pk_add_f32 v[126:127], v[126:127], v[134:135] neg_lo:[0,1] neg_hi:[0,1]
	v_pk_add_f32 v[128:129], v[128:129], v[136:137] neg_lo:[0,1] neg_hi:[0,1]
	v_pk_add_f32 v[130:131], v[130:131], v[138:139] neg_lo:[0,1] neg_hi:[0,1]
	s_waitcnt vmcnt(15)
	v_lshlrev_b32_e32 v132, 16, v100
	v_and_b32_e32 v133, 0xffff0000, v100
	v_lshlrev_b32_e32 v134, 16, v101
	v_and_b32_e32 v135, 0xffff0000, v101
	v_lshlrev_b32_e32 v136, 16, v102
	v_and_b32_e32 v137, 0xffff0000, v102
	v_lshlrev_b32_e32 v138, 16, v103
	v_and_b32_e32 v139, 0xffff0000, v103
	v_pk_add_f32 v[124:125], v[124:125], v[132:133]
	v_pk_add_f32 v[126:127], v[126:127], v[134:135]
	v_pk_add_f32 v[128:129], v[128:129], v[136:137]
	v_pk_add_f32 v[130:131], v[130:131], v[138:139]
	v_pk_fma_f32 v[132:133], v[148:149], v[124:125], v[132:133] neg_lo:[0,0,1] neg_hi:[0,0,1]
	v_pk_fma_f32 v[134:135], v[148:149], v[126:127], v[134:135] neg_lo:[0,0,1] neg_hi:[0,0,1]
	v_pk_fma_f32 v[136:137], v[148:149], v[128:129], v[136:137] neg_lo:[0,0,1] neg_hi:[0,0,1]
	v_pk_fma_f32 v[138:139], v[148:149], v[130:131], v[138:139] neg_lo:[0,0,1] neg_hi:[0,0,1]
	v_cvt_pk_bf16_f32 v140, v132, v133
	v_cvt_pk_bf16_f32 v141, v134, v135
	v_cvt_pk_bf16_f32 v142, v136, v137
	v_cvt_pk_bf16_f32 v143, v138, v139
	v_lshl_add_u64 v[150:151], v[224:225], 0, s[70:71]
	s_add_u32 s70, s70, 0x1000
	global_store_dwordx4 v[150:151], v[140:143], off
	v_cndmask_b32_e64 v144, v96, v88, s[68:69]
	v_cndmask_b32_e64 v145, v97, v89, s[68:69]
	v_cndmask_b32_e64 v146, v98, v90, s[68:69]
	v_cndmask_b32_e64 v147, v99, v91, s[68:69]
	v_lshlrev_b32_e32 v132, 16, v144
	v_and_b32_e32 v133, 0xffff0000, v144
	v_lshlrev_b32_e32 v134, 16, v145
	v_and_b32_e32 v135, 0xffff0000, v145
	v_lshlrev_b32_e32 v136, 16, v146
	v_and_b32_e32 v137, 0xffff0000, v146
	v_lshlrev_b32_e32 v138, 16, v147
	v_and_b32_e32 v139, 0xffff0000, v147
	v_pk_add_f32 v[124:125], v[124:125], v[132:133] neg_lo:[0,1] neg_hi:[0,1]
	v_pk_add_f32 v[126:127], v[126:127], v[134:135] neg_lo:[0,1] neg_hi:[0,1]
	v_pk_add_f32 v[128:129], v[128:129], v[136:137] neg_lo:[0,1] neg_hi:[0,1]
	v_pk_add_f32 v[130:131], v[130:131], v[138:139] neg_lo:[0,1] neg_hi:[0,1]
	s_waitcnt vmcnt(15)
; __device__ __forceinline__ float bf_lo(unsigned w) { return __uint_as_float(w << 16); }
; __device__ __forceinline__ float bf_hi(unsigned w) { return __uint_as_float(w & 0xffff0000u); }
; __device__ __forceinline__ unsigned pk2(float lo, float hi) { return f2bf(lo) | (f2bf(hi) << 16); }
; template <int W> __device__ __forceinline__ void pool_item(const bfu* u, bfu* pooled, int tb) {
;     ...
;     for (int k = 0; k < 8; ++k) {
;         const v4u c = r[W - 1 + k]; const int t = tb + k;
;         const float cv[8] = {pg8::bf_lo(c.x), pg8::bf_hi(c.x), pg8::bf_lo(c.y), pg8::bf_hi(c.y), pg8::bf_lo(c.z), pg8::bf_hi(c.z), pg8::bf_lo(c.w), pg8::bf_hi(c.w)};
; #pragma unroll
;         for (int e = 0; e < 8; ++e) a[e] += cv[e];
;         const float inv = 1.f / (float)((t + 1) < W ? (t + 1) : W);
;         v4u o; o.x = pk2(a[0] * inv - cv[0], a[1] * inv - cv[1]); o.y = pk2(a[2] * inv - cv[2], a[3] * inv - cv[3]); o.z = pk2(a[4] * inv - cv[4], a[5] * inv - cv[5]); o.w = pk2(a[6] * inv - cv[6], a[7] * inv - cv[7]);
;         *(v4u*)(pooled + (size_t)t * 2048) = o;
;         const v4u d = r[k];
;         a[0] -= pg8::bf_lo(d.x); a[1] -= pg8::bf_hi(d.x); a[2] -= pg8::bf_lo(d.y); a[3] -= pg8::bf_hi(d.y); a[4] -= pg8::bf_lo(d.z); a[5] -= pg8::bf_hi(d.z); a[6] -= pg8::bf_lo(d.w); a[7] -= pg8::bf_hi(d.w);
;     }
	v_lshlrev_b32_e32 v132, 16, v104
	v_and_b32_e32 v133, 0xffff0000, v104
	v_lshlrev_b32_e32 v134, 16, v105
	v_and_b32_e32 v135, 0xffff0000, v105
	v_lshlrev_b32_e32 v136, 16, v106
	v_and_b32_e32 v137, 0xffff0000, v106
	v_lshlrev_b32_e32 v138, 16, v107
	v_and_b32_e32 v139, 0xffff0000, v107
	v_pk_add_f32 v[124:125], v[124:125], v[132:133]
	v_pk_add_f32 v[126:127], v[126:127], v[134:135]
	v_pk_add_f32 v[128:129], v[128:129], v[136:137]
	v_pk_add_f32 v[130:131], v[130:131], v[138:139]
	v_pk_fma_f32 v[132:133], v[148:149], v[124:125], v[132:133] neg_lo:[0,0,1] neg_hi:[0,0,1]
	v_pk_fma_f32 v[134:135], v[148:149], v[126:127], v[134:135] neg_lo:[0,0,1] neg_hi:[0,0,1]
	v_pk_fma_f32 v[136:137], v[148:149], v[128:129], v[136:137] neg_lo:[0,0,1] neg_hi:[0,0,1]
	v_pk_fma_f32 v[138:139], v[148:149], v[130:131], v[138:139] neg_lo:[0,0,1] neg_hi:[0,0,1]
	v_cvt_pk_bf16_f32 v140, v132, v133
	v_cvt_pk_bf16_f32 v141, v134, v135
	v_cvt_pk_bf16_f32 v142, v136, v137
	v_cvt_pk_bf16_f32 v143, v138, v139
	v_lshl_add_u64 v[150:151], v[224:225], 0, s[70:71]
	s_add_u32 s70, s70, 0x1000
	global_store_dwordx4 v[150:151], v[140:143], off
	v_cndmask_b32_e64 v144, v100, v92, s[68:69]
	v_cndmask_b32_e64 v145, v101, v93, s[68:69]
	v_cndmask_b32_e64 v146, v102, v94, s[68:69]
	v_cndmask_b32_e64 v147, v103, v95, s[68:69]
	v_lshlrev_b32_e32 v132, 16, v144
	v_and_b32_e32 v133, 0xffff0000, v144
	v_lshlrev_b32_e32 v134, 16, v145
	v_and_b32_e32 v135, 0xffff0000, v145
	v_lshlrev_b32_e32 v136, 16, v146
	v_and_b32_e32 v137, 0xffff0000, v146
	v_lshlrev_b32_e32 v138, 16, v147
	v_and_b32_e32 v139, 0xffff0000, v147
	v_pk_add_f32 v[124:125], v[124:125], v[132:133] neg_lo:[0,1] neg_hi:[0,1]
	v_pk_add_f32 v[126:127], v[126:127], v[134:135] neg_lo:[0,1] neg_hi:[0,1]
	v_pk_add_f32 v[128:129], v[128:129], v[136:137] neg_lo:[0,1] neg_hi:[0,1]
	v_pk_add_f32 v[130:131], v[130:131], v[138:139] neg_lo:[0,1] neg_hi:[0,1]
	s_waitcnt vmcnt(15)
	v_lshlrev_b32_e32 v132, 16, v108
	v_and_b32_e32 v133, 0xffff0000, v108
	v_lshlrev_b32_e32 v134, 16, v109
	v_and_b32_e32 v135, 0xffff0000, v109
	v_lshlrev_b32_e32 v136, 16, v110
	v_and_b32_e32 v137, 0xffff0000, v110
	v_lshlrev_b32_e32 v138, 16, v111
	v_and_b32_e32 v139, 0xffff0000, v111
	v_pk_add_f32 v[124:125], v[124:125], v[132:133]
	v_pk_add_f32 v[126:127], v[126:127], v[134:135]
	v_pk_add_f32 v[128:129], v[128:129], v[136:137]
	v_pk_add_f32 v[130:131], v[130:131], v[138:139]
	v_pk_fma_f32 v[132:133], v[148:149], v[124:125], v[132:133] neg_lo:[0,0,1] neg_hi:[0,0,1]
	v_pk_fma_f32 v[134:135], v[148:149], v[126:127], v[134:135] neg_lo:[0,0,1] neg_hi:[0,0,1]
	v_pk_fma_f32 v[136:137], v[148:149], v[128:129], v[136:137] neg_lo:[0,0,1] neg_hi:[0,0,1]
	v_pk_fma_f32 v[138:139], v[148:149], v[130:131], v[138:139] neg_lo:[0,0,1] neg_hi:[0,0,1]
	v_cvt_pk_bf16_f32 v140, v132, v133
	v_cvt_pk_bf16_f32 v141, v134, v135
	v_cvt_pk_bf16_f32 v142, v136, v137
	v_cvt_pk_bf16_f32 v143, v138, v139
	v_lshl_add_u64 v[150:151], v[224:225], 0, s[70:71]
	s_add_u32 s70, s70, 0x1000
	global_store_dwordx4 v[150:151], v[140:143], off
	v_cndmask_b32_e64 v144, v104, v96, s[68:69]
	v_cndmask_b32_e64 v145, v105, v97, s[68:69]
	v_cndmask_b32_e64 v146, v106, v98, s[68:69]
	v_cndmask_b32_e64 v147, v107, v99, s[68:69]
	v_lshlrev_b32_e32 v132, 16, v144
	v_and_b32_e32 v133, 0xffff0000, v144
	v_lshlrev_b32_e32 v134, 16, v145
	v_and_b32_e32 v135, 0xffff0000, v145
	v_lshlrev_b32_e32 v136, 16, v146
	v_and_b32_e32 v137, 0xffff0000, v146
	v_lshlrev_b32_e32 v138, 16, v147
	v_and_b32_e32 v139, 0xffff0000, v147
	v_pk_add_f32 v[124:125], v[124:125], v[132:133] neg_lo:[0,1] neg_hi:[0,1]
	v_pk_add_f32 v[126:127], v[126:127], v[134:135] neg_lo:[0,1] neg_hi:[0,1]
	v_pk_add_f32 v[128:129], v[128:129], v[136:137] neg_lo:[0,1] neg_hi:[0,1]
	v_pk_add_f32 v[130:131], v[130:131], v[138:139] neg_lo:[0,1] neg_hi:[0,1]
	s_waitcnt vmcnt(15)
; __device__ __forceinline__ float bf_lo(unsigned w) { return __uint_as_float(w << 16); }
; __device__ __forceinline__ float bf_hi(unsigned w) { return __uint_as_float(w & 0xffff0000u); }
; __device__ __forceinline__ unsigned pk2(float lo, float hi) { return f2bf(lo) | (f2bf(hi) << 16); }
; template <int W> __device__ __forceinline__ void pool_item(const bfu* u, bfu* pooled, int tb) {
;     ...
;     for (int k = 0; k < 8; ++k) {
;         const v4u c = r[W - 1 + k]; const int t = tb + k;
;         const float cv[8] = {pg8::bf_lo(c.x), pg8::bf_hi(c.x), pg8::bf_lo(c.y), pg8::bf_hi(c.y), pg8::bf_lo(c.z), pg8::bf_hi(c.z), pg8::bf_lo(c.w), pg8::bf_hi(c.w)};
; #pragma unroll
;         for (int e = 0; e < 8; ++e) a[e] += cv[e];
;         const float inv = 1.f / (float)((t + 1) < W ? (t + 1) : W);
;         v4u o; o.x = pk2(a[0] * inv - cv[0], a[1] * inv - cv[1]); o.y = pk2(a[2] * inv - cv[2], a[3] * inv - cv[3]); o.z = pk2(a[4] * inv - cv[4], a[5] * inv - cv[5]); o.w = pk2(a[6] * inv - cv[6], a[7] * inv - cv[7]);
;         *(v4u*)(pooled + (size_t)t * 2048) = o;
;         const v4u d = r[k];
;         a[0] -= pg8::bf_lo(d.x); a[1] -= pg8::bf_hi(d.x); a[2] -= pg8::bf_lo(d.y); a[3] -= pg8::bf_hi(d.y); a[4] -= pg8::bf_lo(d.z); a[5] -= pg8::bf_hi(d.z); a[6] -= pg8::bf_lo(d.w); a[7] -= pg8::bf_hi(d.w);
;     }
	v_lshlrev_b32_e32 v132, 16, v112
	v_and_b32_e32 v133, 0xffff0000, v112
	v_lshlrev_b32_e32 v134, 16, v113
	v_and_b32_e32 v135, 0xffff0000, v113
	v_lshlrev_b32_e32 v136, 16, v114
	v_and_b32_e32 v137, 0xffff0000, v114
	v_lshlrev_b32_e32 v138, 16, v115
	v_and_b32_e32 v139, 0xffff0000, v115
	v_pk_add_f32 v[124:125], v[124:125], v[132:133]
	v_pk_add_f32 v[126:127], v[126:127], v[134:135]
	v_pk_add_f32 v[128:129], v[128:129], v[136:137]
	v_pk_add_f32 v[130:131], v[130:131], v[138:139]
	v_pk_fma_f32 v[132:133], v[148:149], v[124:125], v[132:133] neg_lo:[0,0,1] neg_hi:[0,0,1]
	v_pk_fma_f32 v[134:135], v[148:149], v[126:127], v[134:135] neg_lo:[0,0,1] neg_hi:[0,0,1]
	v_pk_fma_f32 v[136:137], v[148:149], v[128:129], v[136:137] neg_lo:[0,0,1] neg_hi:[0,0,1]
	v_pk_fma_f32 v[138:139], v[148:149], v[130:131], v[138:139] neg_lo:[0,0,1] neg_hi:[0,0,1]
	v_cvt_pk_bf16_f32 v140, v132, v133
	v_cvt_pk_bf16_f32 v141, v134, v135
	v_cvt_pk_bf16_f32 v142, v136, v137
	v_cvt_pk_bf16_f32 v143, v138, v139
	v_lshl_add_u64 v[150:151], v[224:225], 0, s[70:71]
	s_add_u32 s70, s70, 0x1000
	global_store_dwordx4 v[150:151], v[140:143], off
	v_cndmask_b32_e64 v144, v108, v100, s[68:69]
	v_cndmask_b32_e64 v145, v109, v101, s[68:69]
	v_cndmask_b32_e64 v146, v110, v102, s[68:69]
	v_cndmask_b32_e64 v147, v111, v103, s[68:69]
	v_lshlrev_b32_e32 v132, 16, v144
	v_and_b32_e32 v133, 0xffff0000, v144
	v_lshlrev_b32_e32 v134, 16, v145
	v_and_b32_e32 v135, 0xffff0000, v145
	v_lshlrev_b32_e32 v136, 16, v146
	v_and_b32_e32 v137, 0xffff0000, v146
	v_lshlrev_b32_e32 v138, 16, v147
	v_and_b32_e32 v139, 0xffff0000, v147
	v_pk_add_f32 v[124:125], v[124:125], v[132:133] neg_lo:[0,1] neg_hi:[0,1]
	v_pk_add_f32 v[126:127], v[126:127], v[134:135] neg_lo:[0,1] neg_hi:[0,1]
	v_pk_add_f32 v[128:129], v[128:129], v[136:137] neg_lo:[0,1] neg_hi:[0,1]
	v_pk_add_f32 v[130:131], v[130:131], v[138:139] neg_lo:[0,1] neg_hi:[0,1]
	s_waitcnt vmcnt(15)
	v_lshlrev_b32_e32 v132, 16, v116
	v_and_b32_e32 v133, 0xffff0000, v116
	v_lshlrev_b32_e32 v134, 16, v117
	v_and_b32_e32 v135, 0xffff0000, v117
	v_lshlrev_b32_e32 v136, 16, v118
	v_and_b32_e32 v137, 0xffff0000, v118
	v_lshlrev_b32_e32 v138, 16, v119
	v_and_b32_e32 v139, 0xffff0000, v119
	v_pk_add_f32 v[124:125], v[124:125], v[132:133]
	v_pk_add_f32 v[126:127], v[126:127], v[134:135]
	v_pk_add_f32 v[128:129], v[128:129], v[136:137]
	v_pk_add_f32 v[130:131], v[130:131], v[138:139]
	v_pk_fma_f32 v[132:133], v[148:149], v[124:125], v[132:133] neg_lo:[0,0,1] neg_hi:[0,0,1]
	v_pk_fma_f32 v[134:135], v[148:149], v[126:127], v[134:135] neg_lo:[0,0,1] neg_hi:[0,0,1]
	v_pk_fma_f32 v[136:137], v[148:149], v[128:129], v[136:137] neg_lo:[0,0,1] neg_hi:[0,0,1]
	v_pk_fma_f32 v[138:139], v[148:149], v[130:131], v[138:139] neg_lo:[0,0,1] neg_hi:[0,0,1]
	v_cvt_pk_bf16_f32 v140, v132, v133
	v_cvt_pk_bf16_f32 v141, v134, v135
	v_cvt_pk_bf16_f32 v142, v136, v137
	v_cvt_pk_bf16_f32 v143, v138, v139
	v_lshl_add_u64 v[150:151], v[224:225], 0, s[70:71]
	s_add_u32 s70, s70, 0x1000
	global_store_dwordx4 v[150:151], v[140:143], off
	v_cndmask_b32_e64 v144, v112, v104, s[68:69]
	v_cndmask_b32_e64 v145, v113, v105, s[68:69]
	v_cndmask_b32_e64 v146, v114, v106, s[68:69]
	v_cndmask_b32_e64 v147, v115, v107, s[68:69]
	v_lshlrev_b32_e32 v132, 16, v144
	v_and_b32_e32 v133, 0xffff0000, v144
	v_lshlrev_b32_e32 v134, 16, v145
	v_and_b32_e32 v135, 0xffff0000, v145
	v_lshlrev_b32_e32 v136, 16, v146
	v_and_b32_e32 v137, 0xffff0000, v146
	v_lshlrev_b32_e32 v138, 16, v147
	v_and_b32_e32 v139, 0xffff0000, v147
	v_pk_add_f32 v[124:125], v[124:125], v[132:133] neg_lo:[0,1] neg_hi:[0,1]
	v_pk_add_f32 v[126:127], v[126:127], v[134:135] neg_lo:[0,1] neg_hi:[0,1]
	v_pk_add_f32 v[128:129], v[128:129], v[136:137] neg_lo:[0,1] neg_hi:[0,1]
	v_pk_add_f32 v[130:131], v[130:131], v[138:139] neg_lo:[0,1] neg_hi:[0,1]
	s_waitcnt vmcnt(15)
	v_lshlrev_b32_e32 v132, 16, v120
	v_and_b32_e32 v133, 0xffff0000, v120
	v_lshlrev_b32_e32 v134, 16, v121
	v_and_b32_e32 v135, 0xffff0000, v121
	v_lshlrev_b32_e32 v136, 16, v122
	v_and_b32_e32 v137, 0xffff0000, v122
	v_lshlrev_b32_e32 v138, 16, v123
	v_and_b32_e32 v139, 0xffff0000, v123
	v_pk_add_f32 v[124:125], v[124:125], v[132:133]
	v_pk_add_f32 v[126:127], v[126:127], v[134:135]
	v_pk_add_f32 v[128:129], v[128:129], v[136:137]
	v_pk_add_f32 v[130:131], v[130:131], v[138:139]
	v_pk_fma_f32 v[132:133], v[148:149], v[124:125], v[132:133] neg_lo:[0,0,1] neg_hi:[0,0,1]
	v_pk_fma_f32 v[134:135], v[148:149], v[126:127], v[134:135] neg_lo:[0,0,1] neg_hi:[0,0,1]
	v_pk_fma_f32 v[136:137], v[148:149], v[128:129], v[136:137] neg_lo:[0,0,1] neg_hi:[0,0,1]
	v_pk_fma_f32 v[138:139], v[148:149], v[130:131], v[138:139] neg_lo:[0,0,1] neg_hi:[0,0,1]
	v_cvt_pk_bf16_f32 v140, v132, v133
	v_cvt_pk_bf16_f32 v141, v134, v135
	v_cvt_pk_bf16_f32 v142, v136, v137
	v_cvt_pk_bf16_f32 v143, v138, v139
	v_lshl_add_u64 v[150:151], v[224:225], 0, s[70:71]
	s_add_u32 s70, s70, 0x1000
	global_store_dwordx4 v[150:151], v[140:143], off
	v_cndmask_b32_e64 v144, v116, v108, s[68:69]
	v_cndmask_b32_e64 v145, v117, v109, s[68:69]
	v_cndmask_b32_e64 v146, v118, v110, s[68:69]
	v_cndmask_b32_e64 v147, v119, v111, s[68:69]
	v_lshlrev_b32_e32 v132, 16, v144
	v_and_b32_e32 v133, 0xffff0000, v144
	v_lshlrev_b32_e32 v134, 16, v145
	v_and_b32_e32 v135, 0xffff0000, v145
	v_lshlrev_b32_e32 v136, 16, v146
	v_and_b32_e32 v137, 0xffff0000, v146
	v_lshlrev_b32_e32 v138, 16, v147
	v_and_b32_e32 v139, 0xffff0000, v147
	v_pk_add_f32 v[124:125], v[124:125], v[132:133] neg_lo:[0,1] neg_hi:[0,1]
	v_pk_add_f32 v[126:127], v[126:127], v[134:135] neg_lo:[0,1] neg_hi:[0,1]
	v_pk_add_f32 v[128:129], v[128:129], v[136:137] neg_lo:[0,1] neg_hi:[0,1]
	v_pk_add_f32 v[130:131], v[130:131], v[138:139] neg_lo:[0,1] neg_hi:[0,1]

; __global__ void __launch_bounds__(NWAVES * 64, 2) fwd_megakernel(Args args) {
;     ...
;             if (n >= 768u) {
;                 const int pc = (int)(n - 768u);
; #pragma unroll 1
;                 for (int k2 = 0; k2 < 2; ++k2) { const int i = pc * 1024 + k2 * 512 + (int)threadIdx.x; const int ch = i & 127, tb = (i >> 7) * 8, gidx = ch >> 5;
;                     const bfu* up = Ub + ch * 8; bfu* pp = AB2 + 1024 + ch * 8;
;                     if (gidx == 0) pool_item<2>(up, pp, tb); else if (gidx == 1) pool_item<4>(up, pp, tb); else if (gidx == 2) pool_item<8>(up, pp, tb); else pool_item<16>(up, pp, tb); }
.Lpool_orig:
	v_lshl_add_u32 v142, s86, 10, v158
	s_mov_b32 s4, 0
	s_mov_b64 s[8:9], -1
	s_branch .LBB0_342
